# gemm tile prologue: first-K-tile DMA wait moved to the barrier (accumulator zeroing overlaps the DMA); stale vmcnt waits removed from ffn_up and ffn_down tile headers
# speedup vs baseline: 1.0234x; 1.0048x over previous
.LBB0_248:
	s_mul_hi_i32 s0, s30, 0x38e38e39
	s_lshr_b32 s1, s0, 31
	s_ashr_i32 s31, s0, 4
	s_add_i32 s31, s31, s1
	v_readfirstlane_b32 s5, v128
	s_mul_i32 s0, s31, 0x48
	s_lshr_b32 s16, s5, 1
	s_sub_i32 s4, s30, s0
	s_and_b32 s16, s16, 0x1ffff80
	s_lshl_b32 s0, s4, 19
	v_or_b32_e32 v8, s16, v189
	s_and_b32 s16, s5, 0xc0
	s_lshl_b32 s5, s5, 4
	v_add_u32_e32 v0, s0, v134
	v_lshlrev_b32_e32 v153, 7, v8
	v_or_b32_e32 v8, s16, v189
	s_and_b32 s5, s5, 0x7ffffc00
	v_add_u32_e32 v1, s0, v138
	v_lshl_or_b32 v155, v8, 7, v139
	v_and_b32_e32 v8, 0xfffff870, v0
	s_mov_b32 m0, s5
	v_add_u32_e32 v2, s0, v140
	global_load_lds_dwordx4 v8, s[86:87]
	v_and_b32_e32 v1, 0xfffff870, v1
	s_add_i32 m0, s5, 0x2000
	s_lshl_b32 s1, s31, 19
	v_add_u32_e32 v3, s0, v142
	global_load_lds_dwordx4 v1, s[86:87]
	v_and_b32_e32 v1, 0xfffff870, v2
	s_add_i32 m0, s5, 0x4000
	v_add_u32_e32 v4, s1, v144
	s_add_i32 s16, s5, 0x8000
	global_load_lds_dwordx4 v1, s[86:87]
	v_and_b32_e32 v1, 0xfffff870, v3
	s_add_i32 m0, s5, 0x6000
	v_add_u32_e32 v5, s1, v146
	global_load_lds_dwordx4 v1, s[86:87]
	v_and_b32_e32 v1, 0xfffff870, v4
	s_mov_b32 m0, s16
	v_add_u32_e32 v6, s1, v148
	global_load_lds_dwordx4 v1, s[86:87]
	v_and_b32_e32 v1, 0xfffff870, v5
	s_add_i32 m0, s5, 0xa000
	v_add_u32_e32 v7, s1, v150
	global_load_lds_dwordx4 v1, s[86:87]
	v_and_b32_e32 v1, 0xfffff870, v6
	s_add_i32 m0, s5, 0xc000
	v_and_b32_e32 v136, -16, v0
	global_load_lds_dwordx4 v1, s[86:87]
	v_and_b32_e32 v1, 0xfffff870, v7
	s_add_i32 m0, s5, 0xe000
	v_add_u32_e32 v0, s0, v152
	global_load_lds_dwordx4 v1, s[86:87]
	v_lshl_add_u64 v[162:163], s[14:15], 0, v[136:137]
	v_and_b32_e32 v136, -16, v0
	v_add_u32_e32 v0, s0, v154
	v_lshl_add_u64 v[164:165], s[14:15], 0, v[136:137]
	v_and_b32_e32 v136, -16, v0
	v_add_u32_e32 v0, s0, v156
	v_lshl_add_u64 v[166:167], s[14:15], 0, v[136:137]
	v_and_b32_e32 v136, -16, v0
	v_lshl_add_u64 v[168:169], s[14:15], 0, v[136:137]
	v_and_b32_e32 v136, -16, v4
	v_add_u32_e32 v0, s1, v158
	v_lshl_add_u64 v[170:171], s[14:15], 0, v[136:137]
	v_and_b32_e32 v136, -16, v0
	s_waitcnt vmcnt(8)
	v_lshl_add_u64 v[172:173], s[14:15], 0, v[136:137]
	v_and_b32_e32 v136, -16, v6
	v_add_u32_e32 v0, s1, v160
	v_lshl_add_u64 v[174:175], s[14:15], 0, v[136:137]
	v_and_b32_e32 v136, -16, v0
	v_lshl_add_u64 v[176:177], s[14:15], 0, v[136:137]
	s_mov_b64 s[0:1], 0
	s_mov_b32 s16, s91
	v_mov_b32_e32 v56, v137
	v_mov_b32_e32 v57, v137
	v_mov_b32_e32 v58, v137
	v_mov_b32_e32 v59, v137
	v_mov_b32_e32 v0, v137
	v_mov_b32_e32 v1, v137
	v_mov_b32_e32 v2, v137
	v_mov_b32_e32 v3, v137
	v_mov_b32_e32 v64, v137
	v_mov_b32_e32 v65, v137
	v_mov_b32_e32 v66, v137
	v_mov_b32_e32 v67, v137
	v_mov_b32_e32 v68, v137
	v_mov_b32_e32 v69, v137
	v_mov_b32_e32 v70, v137
	v_mov_b32_e32 v71, v137
	v_mov_b32_e32 v4, v137
	v_mov_b32_e32 v5, v137
	v_mov_b32_e32 v6, v137
	v_mov_b32_e32 v7, v137
	v_mov_b32_e32 v8, v137
	v_mov_b32_e32 v9, v137
	v_mov_b32_e32 v10, v137
	v_mov_b32_e32 v11, v137
	v_mov_b32_e32 v72, v137
	v_mov_b32_e32 v73, v137
	v_mov_b32_e32 v74, v137
	v_mov_b32_e32 v75, v137
	v_mov_b32_e32 v76, v137
	v_mov_b32_e32 v77, v137
	v_mov_b32_e32 v78, v137
	v_mov_b32_e32 v79, v137
	v_mov_b32_e32 v12, v137
	v_mov_b32_e32 v13, v137
	v_mov_b32_e32 v14, v137
	v_mov_b32_e32 v15, v137
	v_mov_b32_e32 v16, v137
	v_mov_b32_e32 v17, v137
	v_mov_b32_e32 v18, v137
	v_mov_b32_e32 v19, v137
	v_mov_b32_e32 v80, v137
	v_mov_b32_e32 v81, v137
	v_mov_b32_e32 v82, v137
	v_mov_b32_e32 v83, v137
	v_mov_b32_e32 v84, v137
	v_mov_b32_e32 v85, v137
	v_mov_b32_e32 v86, v137
	v_mov_b32_e32 v87, v137
	v_mov_b32_e32 v20, v137
	v_mov_b32_e32 v21, v137
	v_mov_b32_e32 v22, v137
	v_mov_b32_e32 v23, v137
	v_mov_b32_e32 v24, v137
	v_mov_b32_e32 v25, v137
	v_mov_b32_e32 v26, v137
	v_mov_b32_e32 v27, v137
	v_mov_b32_e32 v88, v137
	v_mov_b32_e32 v89, v137
	v_mov_b32_e32 v90, v137
	v_mov_b32_e32 v91, v137
	v_mov_b32_e32 v92, v137
	v_mov_b32_e32 v93, v137
	v_mov_b32_e32 v94, v137
	v_mov_b32_e32 v95, v137
	v_mov_b32_e32 v28, v137
	v_mov_b32_e32 v29, v137
	v_mov_b32_e32 v30, v137
	v_mov_b32_e32 v31, v137
	v_mov_b32_e32 v32, v137
	v_mov_b32_e32 v33, v137
	v_mov_b32_e32 v34, v137
	v_mov_b32_e32 v35, v137
	v_mov_b32_e32 v96, v137
	v_mov_b32_e32 v97, v137
	v_mov_b32_e32 v98, v137
	v_mov_b32_e32 v99, v137
	v_mov_b32_e32 v100, v137
	v_mov_b32_e32 v101, v137
	v_mov_b32_e32 v102, v137
	v_mov_b32_e32 v103, v137
	v_mov_b32_e32 v36, v137
	v_mov_b32_e32 v37, v137
	v_mov_b32_e32 v38, v137
	v_mov_b32_e32 v39, v137
	v_mov_b32_e32 v40, v137
	v_mov_b32_e32 v41, v137
	v_mov_b32_e32 v42, v137
	v_mov_b32_e32 v43, v137
	v_mov_b32_e32 v104, v137
	v_mov_b32_e32 v105, v137
	v_mov_b32_e32 v106, v137
	v_mov_b32_e32 v107, v137
	v_mov_b32_e32 v108, v137
	v_mov_b32_e32 v109, v137
	v_mov_b32_e32 v110, v137
	v_mov_b32_e32 v111, v137
	v_mov_b32_e32 v44, v137
	v_mov_b32_e32 v45, v137
	v_mov_b32_e32 v46, v137
	v_mov_b32_e32 v47, v137
	v_mov_b32_e32 v48, v137
	v_mov_b32_e32 v49, v137
	v_mov_b32_e32 v50, v137
	v_mov_b32_e32 v51, v137
	v_mov_b32_e32 v112, v137
	v_mov_b32_e32 v113, v137
	v_mov_b32_e32 v114, v137
	v_mov_b32_e32 v115, v137
	v_mov_b32_e32 v116, v137
	v_mov_b32_e32 v117, v137
	v_mov_b32_e32 v118, v137
	v_mov_b32_e32 v119, v137
	v_mov_b32_e32 v52, v137
	v_mov_b32_e32 v53, v137
	v_mov_b32_e32 v54, v137
	v_mov_b32_e32 v55, v137
	v_mov_b32_e32 v60, v137
	v_mov_b32_e32 v61, v137
	v_mov_b32_e32 v62, v137
	v_mov_b32_e32 v63, v137
	v_mov_b32_e32 v120, v137
	v_mov_b32_e32 v121, v137
	v_mov_b32_e32 v122, v137
	v_mov_b32_e32 v123, v137
	v_mov_b32_e32 v124, v137
	v_mov_b32_e32 v125, v137
	v_mov_b32_e32 v126, v137
	v_mov_b32_e32 v127, v137
	s_waitcnt vmcnt(0) lgkmcnt(0)
	s_barrier
	s_mov_b32 s17, 0x10000
	s_and_b32 s17, s16, 0x10000
	s_xor_b32 s33, s17, 0x10000
	s_add_i32 s33, s5, s33
	s_add_i32 s34, s33, 0x8000
	s_mov_b32 m0, s33
	v_lshl_add_u64 v[254:255], v[162:163], 0, s[0:1]
	global_load_lds_dwordx4 v[254:255], off
	s_add_i32 m0, s33, 0x2000
	v_lshl_add_u64 v[254:255], v[164:165], 0, s[0:1]
	global_load_lds_dwordx4 v[254:255], off
	s_add_i32 m0, s33, 0x4000
	v_lshl_add_u64 v[254:255], v[166:167], 0, s[0:1]
	global_load_lds_dwordx4 v[254:255], off
	s_add_i32 m0, s33, 0x6000
	v_lshl_add_u64 v[254:255], v[168:169], 0, s[0:1]
	global_load_lds_dwordx4 v[254:255], off
	s_mov_b32 m0, s34
	v_lshl_add_u64 v[254:255], v[170:171], 0, s[0:1]
	global_load_lds_dwordx4 v[254:255], off
	s_add_i32 m0, s33, 0xa000
	v_lshl_add_u64 v[254:255], v[172:173], 0, s[0:1]
	global_load_lds_dwordx4 v[254:255], off
	s_add_i32 m0, s33, 0xc000
	v_lshl_add_u64 v[254:255], v[174:175], 0, s[0:1]
	global_load_lds_dwordx4 v[254:255], off
	s_add_i32 m0, s33, 0xe000
	v_lshl_add_u64 v[254:255], v[176:177], 0, s[0:1]
	global_load_lds_dwordx4 v[254:255], off
	v_add3_u32 v253, s17, v153, v129
	ds_read_b128 v[214:217], v253 offset:0x1000
	ds_read_b128 v[218:221], v253 offset:0x1800
	ds_read_b128 v[206:209], v253 offset:0
	v_add3_u32 v253, s17, v155, v129
	ds_read_b128 v[178:181], v253 offset:0
	v_add3_u32 v253, s17, v153, v129
	ds_read_b128 v[210:213], v253 offset:0x800
	v_add3_u32 v253, s17, v155, v129
	ds_read_b128 v[182:185], v253 offset:0x800
	ds_read_b128 v[198:201], v253 offset:0x1000
	ds_read_b128 v[202:205], v253 offset:0x1800
	.p2align 6

.LBB0_742:
	s_ashr_i32 s4, s17, 31
	s_lshr_b32 s4, s4, 26
	s_add_i32 s4, s17, s4
	v_readfirstlane_b32 s9, v128
	s_ashr_i32 s10, s4, 6
	s_andn2_b32 s4, s4, 63
	s_lshr_b32 s11, s9, 1
	s_sub_i32 s8, s17, s4
	s_and_b32 s11, s11, 0x1ffff80
	s_lshl_b32 s4, s8, 19
	v_or_b32_e32 v8, s11, v189
	s_and_b32 s11, s9, 0xc0
	s_lshl_b32 s9, s9, 4
	v_add_u32_e32 v0, s4, v134
	v_lshlrev_b32_e32 v141, 7, v8
	v_or_b32_e32 v8, s11, v189
	s_and_b32 s9, s9, 0x7ffffc00
	v_add_u32_e32 v1, s4, v138
	v_lshl_or_b32 v143, v8, 7, v139
	v_and_b32_e32 v8, 0xfffff870, v0
	s_mov_b32 m0, s9
	v_add_u32_e32 v2, s4, v140
	global_load_lds_dwordx4 v8, s[86:87]
	v_and_b32_e32 v1, 0xfffff870, v1
	s_add_i32 m0, s9, 0x2000
	s_lshl_b32 s5, s10, 19
	v_add_u32_e32 v3, s4, v142
	global_load_lds_dwordx4 v1, s[86:87]
	v_and_b32_e32 v1, 0xfffff870, v2
	s_add_i32 m0, s9, 0x4000
	v_add_u32_e32 v4, s5, v144
	s_add_i32 s11, s9, 0x8000
	global_load_lds_dwordx4 v1, s[86:87]
	v_and_b32_e32 v1, 0xfffff870, v3
	s_add_i32 m0, s9, 0x6000
	v_add_u32_e32 v5, s5, v146
	global_load_lds_dwordx4 v1, s[86:87]
	v_and_b32_e32 v1, 0xfffff870, v4
	s_mov_b32 m0, s11
	v_add_u32_e32 v6, s5, v148
	global_load_lds_dwordx4 v1, s[86:87]
	v_and_b32_e32 v1, 0xfffff870, v5
	s_add_i32 m0, s9, 0xa000
	v_add_u32_e32 v7, s5, v150
	global_load_lds_dwordx4 v1, s[86:87]
	v_and_b32_e32 v1, 0xfffff870, v6
	s_add_i32 m0, s9, 0xc000
	v_and_b32_e32 v136, -16, v0
	global_load_lds_dwordx4 v1, s[86:87]
	v_and_b32_e32 v1, 0xfffff870, v7
	s_add_i32 m0, s9, 0xe000
	v_add_u32_e32 v0, s4, v152
	global_load_lds_dwordx4 v1, s[86:87]
	v_lshl_add_u64 v[162:163], s[6:7], 0, v[136:137]
	v_and_b32_e32 v136, -16, v0
	v_add_u32_e32 v0, s4, v154
	v_lshl_add_u64 v[164:165], s[6:7], 0, v[136:137]
	v_and_b32_e32 v136, -16, v0
	v_add_u32_e32 v0, s4, v156
	v_lshl_add_u64 v[166:167], s[6:7], 0, v[136:137]
	v_and_b32_e32 v136, -16, v0
	v_lshl_add_u64 v[168:169], s[6:7], 0, v[136:137]
	v_and_b32_e32 v136, -16, v4
	v_add_u32_e32 v0, s5, v158
	v_lshl_add_u64 v[170:171], s[6:7], 0, v[136:137]
	v_and_b32_e32 v136, -16, v0
	s_waitcnt vmcnt(8)
	v_lshl_add_u64 v[172:173], s[6:7], 0, v[136:137]
	v_and_b32_e32 v136, -16, v6
	v_add_u32_e32 v0, s5, v160
	v_lshl_add_u64 v[174:175], s[6:7], 0, v[136:137]
	v_and_b32_e32 v136, -16, v0
	v_lshl_add_u64 v[176:177], s[6:7], 0, v[136:137]
	s_mov_b64 s[4:5], 0
	s_mov_b32 s11, 0
	s_mov_b32 s18, 0
	v_mov_b32_e32 v56, 0
	v_mov_b32_e32 v57, v137
	v_mov_b32_e32 v58, v137
	v_mov_b32_e32 v59, v137
	v_mov_b32_e32 v52, 0
	v_mov_b32_e32 v53, v137
	v_mov_b32_e32 v54, v137
	v_mov_b32_e32 v55, v137
	v_mov_b32_e32 v64, 0
	v_mov_b32_e32 v65, v137
	v_mov_b32_e32 v66, v137
	v_mov_b32_e32 v67, v137
	v_mov_b32_e32 v68, 0
	v_mov_b32_e32 v69, v137
	v_mov_b32_e32 v70, v137
	v_mov_b32_e32 v71, v137
	v_mov_b32_e32 v0, 0
	v_mov_b32_e32 v1, v137
	v_mov_b32_e32 v2, v137
	v_mov_b32_e32 v3, v137
	v_mov_b32_e32 v4, 0
	v_mov_b32_e32 v5, v137
	v_mov_b32_e32 v6, v137
	v_mov_b32_e32 v7, v137
	v_mov_b32_e32 v72, 0
	v_mov_b32_e32 v73, v137
	v_mov_b32_e32 v74, v137
	v_mov_b32_e32 v75, v137
	v_mov_b32_e32 v76, 0
	v_mov_b32_e32 v77, v137
	v_mov_b32_e32 v78, v137
	v_mov_b32_e32 v79, v137
	v_mov_b32_e32 v8, 0
	v_mov_b32_e32 v9, v137
	v_mov_b32_e32 v10, v137
	v_mov_b32_e32 v11, v137
	v_mov_b32_e32 v12, 0
	v_mov_b32_e32 v13, v137
	v_mov_b32_e32 v14, v137
	v_mov_b32_e32 v15, v137
	v_mov_b32_e32 v80, 0
	v_mov_b32_e32 v81, v137
	v_mov_b32_e32 v82, v137
	v_mov_b32_e32 v83, v137
	v_mov_b32_e32 v84, 0
	v_mov_b32_e32 v85, v137
	v_mov_b32_e32 v86, v137
	v_mov_b32_e32 v87, v137
	v_mov_b32_e32 v16, 0
	v_mov_b32_e32 v17, v137
	v_mov_b32_e32 v18, v137
	v_mov_b32_e32 v19, v137
	v_mov_b32_e32 v20, 0
	v_mov_b32_e32 v21, v137
	v_mov_b32_e32 v22, v137
	v_mov_b32_e32 v23, v137
	v_mov_b32_e32 v88, 0
	v_mov_b32_e32 v89, v137
	v_mov_b32_e32 v90, v137
	v_mov_b32_e32 v91, v137
	v_mov_b32_e32 v92, 0
	v_mov_b32_e32 v93, v137
	v_mov_b32_e32 v94, v137
	v_mov_b32_e32 v95, v137
	v_mov_b32_e32 v24, 0
	v_mov_b32_e32 v25, v137
	v_mov_b32_e32 v26, v137
	v_mov_b32_e32 v27, v137
	v_mov_b32_e32 v28, 0
	v_mov_b32_e32 v29, v137
	v_mov_b32_e32 v30, v137
	v_mov_b32_e32 v31, v137
	v_mov_b32_e32 v96, 0
	v_mov_b32_e32 v97, v137
	v_mov_b32_e32 v98, v137
	v_mov_b32_e32 v99, v137
	v_mov_b32_e32 v100, 0
	v_mov_b32_e32 v101, v137
	v_mov_b32_e32 v102, v137
	v_mov_b32_e32 v103, v137
	v_mov_b32_e32 v32, 0
	v_mov_b32_e32 v33, v137
	v_mov_b32_e32 v34, v137
	v_mov_b32_e32 v35, v137
	v_mov_b32_e32 v36, 0
	v_mov_b32_e32 v37, v137
	v_mov_b32_e32 v38, v137
	v_mov_b32_e32 v39, v137
	v_mov_b32_e32 v104, 0
	v_mov_b32_e32 v105, v137
	v_mov_b32_e32 v106, v137
	v_mov_b32_e32 v107, v137
	v_mov_b32_e32 v108, 0
	v_mov_b32_e32 v109, v137
	v_mov_b32_e32 v110, v137
	v_mov_b32_e32 v111, v137
	v_mov_b32_e32 v40, 0
	v_mov_b32_e32 v41, v137
	v_mov_b32_e32 v42, v137
	v_mov_b32_e32 v43, v137
	v_mov_b32_e32 v44, 0
	v_mov_b32_e32 v45, v137
	v_mov_b32_e32 v46, v137
	v_mov_b32_e32 v47, v137
	v_mov_b32_e32 v112, 0
	v_mov_b32_e32 v113, v137
	v_mov_b32_e32 v114, v137
	v_mov_b32_e32 v115, v137
	v_mov_b32_e32 v116, 0
	v_mov_b32_e32 v117, v137
	v_mov_b32_e32 v118, v137
	v_mov_b32_e32 v119, v137
	v_mov_b32_e32 v48, 0
	v_mov_b32_e32 v49, v137
	v_mov_b32_e32 v50, v137
	v_mov_b32_e32 v51, v137
	v_mov_b32_e32 v60, 0
	v_mov_b32_e32 v61, v137
	v_mov_b32_e32 v62, v137
	v_mov_b32_e32 v63, v137
	v_mov_b32_e32 v120, 0
	v_mov_b32_e32 v121, v137
	v_mov_b32_e32 v122, v137
	v_mov_b32_e32 v123, v137
	v_mov_b32_e32 v124, 0
	v_mov_b32_e32 v125, v137
	v_mov_b32_e32 v126, v137
	v_mov_b32_e32 v127, v137
	s_waitcnt vmcnt(0) lgkmcnt(0)
	s_barrier
	s_and_b32 s19, s11, 0x10000
	s_xor_b32 s24, s19, 0x10000
	s_add_i32 s24, s9, s24
	s_add_i32 s25, s24, 0x8000
	s_mov_b32 m0, s24
	v_lshl_add_u64 v[254:255], v[162:163], 0, s[4:5]
	global_load_lds_dwordx4 v[254:255], off
	s_add_i32 m0, s24, 0x2000
	v_lshl_add_u64 v[254:255], v[164:165], 0, s[4:5]
	global_load_lds_dwordx4 v[254:255], off
	s_add_i32 m0, s24, 0x4000
	v_lshl_add_u64 v[254:255], v[166:167], 0, s[4:5]
	global_load_lds_dwordx4 v[254:255], off
	s_add_i32 m0, s24, 0x6000
	v_lshl_add_u64 v[254:255], v[168:169], 0, s[4:5]
	global_load_lds_dwordx4 v[254:255], off
	s_mov_b32 m0, s25
	v_lshl_add_u64 v[254:255], v[170:171], 0, s[4:5]
	global_load_lds_dwordx4 v[254:255], off
	s_add_i32 m0, s24, 0xa000
	v_lshl_add_u64 v[254:255], v[172:173], 0, s[4:5]
	global_load_lds_dwordx4 v[254:255], off
	s_add_i32 m0, s24, 0xc000
	v_lshl_add_u64 v[254:255], v[174:175], 0, s[4:5]
	global_load_lds_dwordx4 v[254:255], off
	s_add_i32 m0, s24, 0xe000
	v_lshl_add_u64 v[254:255], v[176:177], 0, s[4:5]
	global_load_lds_dwordx4 v[254:255], off
	v_add3_u32 v253, s19, v141, v129
	ds_read_b128 v[214:217], v253 offset:0x1000
	ds_read_b128 v[218:221], v253 offset:0x1800
	ds_read_b128 v[206:209], v253 offset:0
	v_add3_u32 v253, s19, v143, v129
	ds_read_b128 v[178:181], v253 offset:0
	v_add3_u32 v253, s19, v141, v129
	ds_read_b128 v[210:213], v253 offset:0x800
	v_add3_u32 v253, s19, v143, v129
	ds_read_b128 v[182:185], v253 offset:0x800
	ds_read_b128 v[198:201], v253 offset:0x1000
	ds_read_b128 v[202:205], v253 offset:0x1800
	.p2align 6

.LBB0_996:
	v_or_b32_e32 v3, s5, v137
	v_cmp_lt_i32_e32 vcc, s13, v3
	s_and_saveexec_b64 s[0:1], vcc
	s_xor_b64 s[0:1], exec, s[0:1]
	v_add_u32_e32 v1, 0xffffff78, v3
	v_mul_hi_u32 v0, v1, s12
	v_lshrrev_b32_e32 v2, 1, v0
	v_lshl_add_u32 v0, v2, 8, v149
	v_lshl_add_u32 v2, v2, 1, v2
	v_sub_u32_e32 v1, v1, v2
	s_or_saveexec_b64 s[0:1], s[0:1]
	v_mov_b32_e32 v2, 0x100
	s_xor_b64 exec, exec, s[0:1]
	v_mul_hi_i32 v0, v3, s14
	v_lshrrev_b32_e32 v1, 31, v0
	v_ashrrev_i32_e32 v0, 3, v0
	v_add_u32_e32 v1, v0, v1
	v_lshlrev_b32_e32 v0, 11, v1
	v_lshl_add_u32 v1, v1, 4, v1
	v_sub_u32_e32 v1, v3, v1
	v_mov_b32_e32 v2, 0x800
	s_or_b64 exec, exec, s[0:1]
	s_or_b32 s28, s5, 1
	s_cmpk_gt_i32 s28, 0x87
	s_mov_b64 s[0:1], -1
	s_cbranch_scc0 .LBB0_1002
	s_add_i32 s0, s5, 0x79
	s_and_b32 s1, s0, 0xff
	s_mulk_i32 s1, 0xab
	s_bfe_u32 s1, s1, 0x70009
	s_lshl_b32 s25, s1, 8
	s_mul_i32 s1, s1, 3
	s_sub_i32 s0, s0, s1
	s_addk_i32 s25, 0x4000
	s_and_b32 s27, s0, 0xff
	s_mov_b64 s[0:1], 0

.LBB0_1004:
	v_add_u32_e32 v6, s5, v139
	v_cmp_lt_i32_e32 vcc, s13, v6
	s_and_saveexec_b64 s[0:1], vcc
	s_xor_b64 s[0:1], exec, s[0:1]
	v_add_u32_e32 v4, 0xffffff78, v6
	v_mul_hi_u32 v3, v4, s12
	v_lshrrev_b32_e32 v5, 1, v3
	v_lshl_add_u32 v3, v5, 8, v149
	v_lshl_add_u32 v5, v5, 1, v5
	v_sub_u32_e32 v4, v4, v5
	s_or_saveexec_b64 s[0:1], s[0:1]
	v_mov_b32_e32 v5, 0x100
	s_xor_b64 exec, exec, s[0:1]
	v_mul_hi_i32 v3, v6, s14
	v_lshrrev_b32_e32 v4, 31, v3
	v_ashrrev_i32_e32 v3, 3, v3
	v_add_u32_e32 v4, v3, v4
	v_lshlrev_b32_e32 v3, 11, v4
	v_lshl_add_u32 v4, v4, 4, v4
	v_sub_u32_e32 v4, v6, v4
	v_mov_b32_e32 v5, 0x800
	s_or_b64 exec, exec, s[0:1]
	s_mul_i32 s0, s27, 0x7e
	v_add_u32_e32 v8, s0, v129
	v_add_u32_e32 v6, s25, v8
	v_lshl_add_u32 v9, v6, 11, v136
	v_mad_u64_u32 v[6:7], s[0:1], v1, s15, v[138:139]
	s_mul_i32 s0, s7, 0x7e
	v_add_u32_e32 v0, v6, v0
	v_add_u32_e32 v10, s0, v129
	v_lshl_add_u32 v7, v0, 11, v140
	v_add_u32_e32 v0, s6, v10
	v_lshl_add_u32 v11, v0, 11, v136
	v_mad_u64_u32 v[0:1], s[0:1], v4, s15, v[142:143]
	v_cmp_gt_u32_e32 vcc, s24, v10
	v_add_u32_e32 v1, v0, v3
	v_readfirstlane_b32 s0, v128
	v_cndmask_b32_e32 v3, v145, v11, vcc
	v_cmp_lt_u32_e32 vcc, v6, v2
	s_lshr_b32 s1, s0, 1
	v_lshl_add_u32 v1, v1, 11, v144
	v_cndmask_b32_e32 v2, v145, v7, vcc
	v_cmp_gt_u32_e32 vcc, s26, v8
	v_subrev_u32_e32 v134, s86, v3
	s_and_b32 s1, s1, 0x1ffff80
	v_cndmask_b32_e32 v3, v145, v9, vcc
	v_cmp_lt_u32_e32 vcc, v0, v5
	v_subrev_u32_e32 v2, s86, v2
	s_lshl_b32 s7, s4, 19
	v_cndmask_b32_e32 v0, v145, v1, vcc
	v_or_b32_e32 v1, s1, v189
	s_and_b32 s1, s0, 0xc0
	s_lshl_b32 s0, s0, 4
	s_and_b32 s6, s0, 0x7ffffc00
	s_mov_b32 m0, s6
	v_subrev_u32_e32 v4, s86, v3
	global_load_lds_dwordx4 v134, s[86:87]
	s_add_i32 m0, s6, 0x2000
	v_subrev_u32_e32 v0, s86, v0
	global_load_lds_dwordx4 v2, s[86:87]
	s_add_i32 m0, s6, 0x4000
	v_add_u32_e32 v6, s7, v146
	s_add_i32 s0, s6, 0x8000
	global_load_lds_dwordx4 v4, s[86:87]
	s_add_i32 m0, s6, 0x6000
	v_add_u32_e32 v8, s7, v148
	global_load_lds_dwordx4 v0, s[86:87]
	v_and_b32_e32 v6, 0xfffff870, v6
	s_mov_b32 m0, s0
	v_add_u32_e32 v9, s7, v150
	global_load_lds_dwordx4 v6, s[86:87]
	v_and_b32_e32 v8, 0xfffff870, v8
	s_add_i32 m0, s6, 0xa000
	v_add_u32_e32 v10, s7, v152
	global_load_lds_dwordx4 v8, s[86:87]
	v_and_b32_e32 v8, 0xfffff870, v9
	s_add_i32 m0, s6, 0xc000
	v_and_b32_e32 v10, 0xfffff870, v10
	global_load_lds_dwordx4 v8, s[86:87]
	s_add_i32 m0, s6, 0xe000
	v_lshlrev_b32_e32 v155, 7, v1
	global_load_lds_dwordx4 v10, s[86:87]
	v_or_b32_e32 v1, s1, v189
	v_lshl_or_b32 v172, v1, 7, v147
	v_mov_b32_e32 v1, v135
	v_lshl_add_u64 v[162:163], s[56:57], 0, v[0:1]
	v_add_u32_e32 v0, s7, v154
	v_mov_b32_e32 v3, v135
	v_mov_b32_e32 v5, v135
	v_mov_b32_e32 v7, v135
	v_mov_b32_e32 v9, v135
	v_mov_b32_e32 v11, v135
	v_lshl_add_u64 v[156:157], s[56:57], 0, v[134:135]
	v_and_b32_e32 v134, -16, v0
	v_mov_b32_e32 v52, 0
	v_lshl_add_u64 v[158:159], s[56:57], 0, v[2:3]
	v_lshl_add_u64 v[160:161], s[56:57], 0, v[4:5]
	v_lshl_add_u64 v[164:165], s[56:57], 0, v[6:7]
	v_lshl_add_u64 v[166:167], s[56:57], 0, v[134:135]
	v_lshl_add_u64 v[168:169], s[56:57], 0, v[8:9]
	v_lshl_add_u64 v[170:171], s[56:57], 0, v[10:11]
	s_mov_b32 s7, 0
	s_mov_b64 s[0:1], 0
	v_mov_b32_e32 v53, v52
	v_mov_b32_e32 v54, v52
	v_mov_b32_e32 v55, v52
	v_mov_b32_e32 v0, v52
	v_mov_b32_e32 v1, v52
	v_mov_b32_e32 v2, v52
	v_mov_b32_e32 v3, v52
	v_mov_b32_e32 v64, v52
	v_mov_b32_e32 v65, v52
	v_mov_b32_e32 v66, v52
	v_mov_b32_e32 v67, v52
	v_mov_b32_e32 v68, v52
	v_mov_b32_e32 v69, v52
	v_mov_b32_e32 v70, v52
	v_mov_b32_e32 v71, v52
	v_mov_b32_e32 v4, v52
	v_mov_b32_e32 v5, v52
	v_mov_b32_e32 v6, v52
	v_mov_b32_e32 v7, v52
	v_mov_b32_e32 v8, v52
	v_mov_b32_e32 v9, v52
	v_mov_b32_e32 v10, v52
	v_mov_b32_e32 v11, v52
	v_mov_b32_e32 v72, v52
	v_mov_b32_e32 v73, v52
	v_mov_b32_e32 v74, v52
	v_mov_b32_e32 v75, v52
	v_mov_b32_e32 v76, v52
	v_mov_b32_e32 v77, v52
	v_mov_b32_e32 v78, v52
	v_mov_b32_e32 v79, v52
	v_mov_b32_e32 v12, v52
	v_mov_b32_e32 v13, v52
	v_mov_b32_e32 v14, v52
	v_mov_b32_e32 v15, v52
	v_mov_b32_e32 v16, v52
	v_mov_b32_e32 v17, v52
	v_mov_b32_e32 v18, v52
	v_mov_b32_e32 v19, v52
	v_mov_b32_e32 v80, v52
	v_mov_b32_e32 v81, v52
	v_mov_b32_e32 v82, v52
	v_mov_b32_e32 v83, v52
	v_mov_b32_e32 v84, v52
	v_mov_b32_e32 v85, v52
	v_mov_b32_e32 v86, v52
	v_mov_b32_e32 v87, v52
	v_mov_b32_e32 v20, v52
	v_mov_b32_e32 v21, v52
	v_mov_b32_e32 v22, v52
	v_mov_b32_e32 v23, v52
	v_mov_b32_e32 v24, v52
	v_mov_b32_e32 v25, v52
	v_mov_b32_e32 v26, v52
	v_mov_b32_e32 v27, v52
	v_mov_b32_e32 v88, v52
	v_mov_b32_e32 v89, v52
	v_mov_b32_e32 v90, v52
	v_mov_b32_e32 v91, v52
	v_mov_b32_e32 v92, v52
	v_mov_b32_e32 v93, v52
	v_mov_b32_e32 v94, v52
	v_mov_b32_e32 v95, v52
	v_mov_b32_e32 v28, v52
	v_mov_b32_e32 v29, v52
	v_mov_b32_e32 v30, v52
	v_mov_b32_e32 v31, v52
	v_mov_b32_e32 v32, v52
	v_mov_b32_e32 v33, v52
	v_mov_b32_e32 v34, v52
	v_mov_b32_e32 v35, v52
	v_mov_b32_e32 v96, v52
	v_mov_b32_e32 v97, v52
	v_mov_b32_e32 v98, v52
	v_mov_b32_e32 v99, v52
	v_mov_b32_e32 v100, v52
	v_mov_b32_e32 v101, v52
	v_mov_b32_e32 v102, v52
	v_mov_b32_e32 v103, v52
	v_mov_b32_e32 v36, v52
	v_mov_b32_e32 v37, v52
	v_mov_b32_e32 v38, v52
	v_mov_b32_e32 v39, v52
	v_mov_b32_e32 v40, v52
	v_mov_b32_e32 v41, v52
	v_mov_b32_e32 v42, v52
	v_mov_b32_e32 v43, v52
	v_mov_b32_e32 v104, v52
	v_mov_b32_e32 v105, v52
	v_mov_b32_e32 v106, v52
	v_mov_b32_e32 v107, v52
	v_mov_b32_e32 v108, v52
	v_mov_b32_e32 v109, v52
	v_mov_b32_e32 v110, v52
	v_mov_b32_e32 v111, v52
	v_mov_b32_e32 v44, v52
	v_mov_b32_e32 v45, v52
	v_mov_b32_e32 v46, v52
	v_mov_b32_e32 v47, v52
	v_mov_b32_e32 v48, v52
	v_mov_b32_e32 v49, v52
	v_mov_b32_e32 v50, v52
	v_mov_b32_e32 v51, v52
	v_mov_b32_e32 v112, v52
	v_mov_b32_e32 v113, v52
	v_mov_b32_e32 v114, v52
	v_mov_b32_e32 v115, v52
	v_mov_b32_e32 v116, v52
	v_mov_b32_e32 v117, v52
	v_mov_b32_e32 v118, v52
	v_mov_b32_e32 v119, v52
	v_mov_b32_e32 v56, v52
	v_mov_b32_e32 v57, v52
	v_mov_b32_e32 v58, v52
	v_mov_b32_e32 v59, v52
	v_mov_b32_e32 v60, v52
	v_mov_b32_e32 v61, v52
	v_mov_b32_e32 v62, v52
	v_mov_b32_e32 v63, v52
	v_mov_b32_e32 v120, v52
	v_mov_b32_e32 v121, v52
	v_mov_b32_e32 v122, v52
	v_mov_b32_e32 v123, v52
	v_mov_b32_e32 v124, v52
	v_mov_b32_e32 v125, v52
	v_mov_b32_e32 v126, v52
	v_mov_b32_e32 v127, v52
	s_waitcnt vmcnt(0) lgkmcnt(0)
	s_barrier
	s_mov_b32 s24, 0x10000
	s_and_b32 s24, s7, 0x10000
	s_xor_b32 s25, s24, 0x10000
	s_add_i32 s25, s6, s25
	s_add_i32 s26, s25, 0x8000
	s_mov_b32 m0, s25
	v_lshl_add_u64 v[254:255], v[156:157], 0, s[0:1]
	global_load_lds_dwordx4 v[254:255], off
	s_add_i32 m0, s25, 0x2000
	v_lshl_add_u64 v[254:255], v[158:159], 0, s[0:1]
	global_load_lds_dwordx4 v[254:255], off
	s_add_i32 m0, s25, 0x4000
	v_lshl_add_u64 v[254:255], v[160:161], 0, s[0:1]
	global_load_lds_dwordx4 v[254:255], off
	s_add_i32 m0, s25, 0x6000
	v_lshl_add_u64 v[254:255], v[162:163], 0, s[0:1]
	global_load_lds_dwordx4 v[254:255], off
	s_mov_b32 m0, s26
	v_lshl_add_u64 v[254:255], v[164:165], 0, s[0:1]
	global_load_lds_dwordx4 v[254:255], off
	s_add_i32 m0, s25, 0xa000
	v_lshl_add_u64 v[254:255], v[166:167], 0, s[0:1]
	global_load_lds_dwordx4 v[254:255], off
	s_add_i32 m0, s25, 0xc000
	v_lshl_add_u64 v[254:255], v[168:169], 0, s[0:1]
	global_load_lds_dwordx4 v[254:255], off
	s_add_i32 m0, s25, 0xe000
	v_lshl_add_u64 v[254:255], v[170:171], 0, s[0:1]
	global_load_lds_dwordx4 v[254:255], off
	v_add3_u32 v253, s24, v155, v141
	ds_read_b128 v[210:213], v253 offset:0x1000
	ds_read_b128 v[214:217], v253 offset:0x1800
	ds_read_b128 v[202:205], v253 offset:0
	v_add3_u32 v253, s24, v172, v141
	ds_read_b128 v[174:177], v253 offset:0
	v_add3_u32 v253, s24, v155, v141
	ds_read_b128 v[206:209], v253 offset:0x800
	v_add3_u32 v253, s24, v172, v141
	ds_read_b128 v[178:181], v253 offset:0x800
	ds_read_b128 v[182:185], v253 offset:0x1000
	ds_read_b128 v[198:201], v253 offset:0x1800
	.p2align 6

.LBB0_1191:
	s_ashr_i32 s6, s17, 31
	s_lshr_b32 s6, s6, 26
	s_add_i32 s6, s17, s6
	s_ashr_i32 s12, s6, 6
	s_andn2_b32 s6, s6, 63
	s_sub_i32 s10, s17, s6
	s_mul_i32 s6, s10, 0xb0000
	v_readfirstlane_b32 s11, v128
	s_lshl_b32 s13, s6, 1
	v_or_b32_e32 v3, s6, v134
	s_lshr_b32 s6, s11, 1
	s_and_b32 s6, s6, 0x1ffff80
	v_lshl_add_u32 v4, v3, 1, v144
	v_or_b32_e32 v3, s6, v189
	s_and_b32 s6, s11, 0xc0
	v_lshlrev_b32_e32 v141, 7, v3
	v_or_b32_e32 v3, s6, v189
	s_lshl_b32 s6, s11, 4
	v_add_u32_e32 v0, s13, v138
	s_and_b32 s11, s6, 0x7ffffc00
	v_add_u32_e32 v1, s13, v140
	v_and_b32_e32 v136, 0xfffffe70, v0
	s_mov_b32 m0, s11
	v_add_u32_e32 v2, s13, v142
	global_load_lds_dwordx4 v136, s[86:87]
	v_and_b32_e32 v0, 0xfffffe70, v1
	s_add_i32 m0, s11, 0x2000
	s_mul_i32 s7, s12, 0x160000
	global_load_lds_dwordx4 v0, s[86:87]
	v_and_b32_e32 v2, 0xfffffe70, v2
	s_add_i32 m0, s11, 0x4000
	v_add_u32_e32 v6, s7, v146
	s_add_i32 s6, s11, 0x8000
	global_load_lds_dwordx4 v2, s[86:87]
	v_and_b32_e32 v4, 0xfffffe70, v4
	s_add_i32 m0, s11, 0x6000
	v_add_u32_e32 v8, s7, v148
	global_load_lds_dwordx4 v4, s[86:87]
	v_and_b32_e32 v6, 0xfffffe70, v6
	s_mov_b32 m0, s6
	v_add_u32_e32 v10, s7, v150
	global_load_lds_dwordx4 v6, s[86:87]
	v_and_b32_e32 v8, 0xfffffe70, v8
	s_add_i32 m0, s11, 0xa000
	v_add_u32_e32 v12, s7, v152
	global_load_lds_dwordx4 v8, s[86:87]
	v_and_b32_e32 v10, 0xfffffe70, v10
	s_add_i32 m0, s11, 0xc000
	v_and_b32_e32 v12, 0xfffffe70, v12
	global_load_lds_dwordx4 v10, s[86:87]
	s_add_i32 m0, s11, 0xe000
	v_lshl_or_b32 v143, v3, 7, v139
	global_load_lds_dwordx4 v12, s[86:87]
	s_waitcnt vmcnt(8)
	v_mov_b32_e32 v1, v137
	v_mov_b32_e32 v3, v137
	v_mov_b32_e32 v5, v137
	v_mov_b32_e32 v7, v137
	v_mov_b32_e32 v9, v137
	v_mov_b32_e32 v11, v137
	v_mov_b32_e32 v13, v137
	v_lshl_add_u64 v[154:155], s[8:9], 0, v[136:137]
	v_lshl_add_u64 v[156:157], s[8:9], 0, v[0:1]
	v_lshl_add_u64 v[158:159], s[8:9], 0, v[2:3]
	v_lshl_add_u64 v[160:161], s[8:9], 0, v[4:5]
	v_lshl_add_u64 v[162:163], s[8:9], 0, v[6:7]
	v_lshl_add_u64 v[164:165], s[8:9], 0, v[8:9]
	v_lshl_add_u64 v[166:167], s[8:9], 0, v[10:11]
	v_lshl_add_u64 v[168:169], s[8:9], 0, v[12:13]
	s_mov_b64 s[6:7], 0
	s_mov_b32 s13, 0
	s_mov_b32 s20, 0
	v_mov_b32_e32 v56, 0
	v_mov_b32_e32 v57, v137
	v_mov_b32_e32 v58, v137
	v_mov_b32_e32 v59, v137
	v_mov_b32_e32 v52, 0
	v_mov_b32_e32 v53, v137
	v_mov_b32_e32 v54, v137
	v_mov_b32_e32 v55, v137
	v_mov_b32_e32 v64, 0
	v_mov_b32_e32 v65, v137
	v_mov_b32_e32 v66, v137
	v_mov_b32_e32 v67, v137
	v_mov_b32_e32 v68, 0
	v_mov_b32_e32 v69, v137
	v_mov_b32_e32 v70, v137
	v_mov_b32_e32 v71, v137
	v_mov_b32_e32 v0, 0
	v_mov_b32_e32 v2, v137
	v_mov_b32_e32 v4, 0
	v_mov_b32_e32 v6, v137
	v_mov_b32_e32 v72, 0
	v_mov_b32_e32 v73, v137
	v_mov_b32_e32 v74, v137
	v_mov_b32_e32 v75, v137
	v_mov_b32_e32 v76, 0
	v_mov_b32_e32 v77, v137
	v_mov_b32_e32 v78, v137
	v_mov_b32_e32 v79, v137
	v_mov_b32_e32 v8, 0
	v_mov_b32_e32 v10, v137
	v_mov_b32_e32 v12, 0
	v_mov_b32_e32 v14, v137
	v_mov_b32_e32 v15, v137
	v_mov_b32_e32 v80, 0
	v_mov_b32_e32 v81, v137
	v_mov_b32_e32 v82, v137
	v_mov_b32_e32 v83, v137
	v_mov_b32_e32 v84, 0
	v_mov_b32_e32 v85, v137
	v_mov_b32_e32 v86, v137
	v_mov_b32_e32 v87, v137
	v_mov_b32_e32 v16, 0
	v_mov_b32_e32 v17, v137
	v_mov_b32_e32 v18, v137
	v_mov_b32_e32 v19, v137
	v_mov_b32_e32 v20, 0
	v_mov_b32_e32 v21, v137
	v_mov_b32_e32 v22, v137
	v_mov_b32_e32 v23, v137
	v_mov_b32_e32 v88, 0
	v_mov_b32_e32 v89, v137
	v_mov_b32_e32 v90, v137
	v_mov_b32_e32 v91, v137
	v_mov_b32_e32 v92, 0
	v_mov_b32_e32 v93, v137
	v_mov_b32_e32 v94, v137
	v_mov_b32_e32 v95, v137
	v_mov_b32_e32 v24, 0
	v_mov_b32_e32 v25, v137
	v_mov_b32_e32 v26, v137
	v_mov_b32_e32 v27, v137
	v_mov_b32_e32 v28, 0
	v_mov_b32_e32 v29, v137
	v_mov_b32_e32 v30, v137
	v_mov_b32_e32 v31, v137
	v_mov_b32_e32 v96, 0
	v_mov_b32_e32 v97, v137
	v_mov_b32_e32 v98, v137
	v_mov_b32_e32 v99, v137
	v_mov_b32_e32 v100, 0
	v_mov_b32_e32 v101, v137
	v_mov_b32_e32 v102, v137
	v_mov_b32_e32 v103, v137
	v_mov_b32_e32 v32, 0
	v_mov_b32_e32 v33, v137
	v_mov_b32_e32 v34, v137
	v_mov_b32_e32 v35, v137
	v_mov_b32_e32 v36, 0
	v_mov_b32_e32 v37, v137
	v_mov_b32_e32 v38, v137
	v_mov_b32_e32 v39, v137
	v_mov_b32_e32 v104, 0
	v_mov_b32_e32 v105, v137
	v_mov_b32_e32 v106, v137
	v_mov_b32_e32 v107, v137
	v_mov_b32_e32 v108, 0
	v_mov_b32_e32 v109, v137
	v_mov_b32_e32 v110, v137
	v_mov_b32_e32 v111, v137
	v_mov_b32_e32 v40, 0
	v_mov_b32_e32 v41, v137
	v_mov_b32_e32 v42, v137
	v_mov_b32_e32 v43, v137
	v_mov_b32_e32 v44, 0
	v_mov_b32_e32 v45, v137
	v_mov_b32_e32 v46, v137
	v_mov_b32_e32 v47, v137
	v_mov_b32_e32 v112, 0
	v_mov_b32_e32 v113, v137
	v_mov_b32_e32 v114, v137
	v_mov_b32_e32 v115, v137
	v_mov_b32_e32 v116, 0
	v_mov_b32_e32 v117, v137
	v_mov_b32_e32 v118, v137
	v_mov_b32_e32 v119, v137
	v_mov_b32_e32 v48, 0
	v_mov_b32_e32 v49, v137
	v_mov_b32_e32 v50, v137
	v_mov_b32_e32 v51, v137
	v_mov_b32_e32 v60, 0
	v_mov_b32_e32 v61, v137
	v_mov_b32_e32 v62, v137
	v_mov_b32_e32 v63, v137
	v_mov_b32_e32 v120, 0
	v_mov_b32_e32 v121, v137
	v_mov_b32_e32 v122, v137
	v_mov_b32_e32 v123, v137
	v_mov_b32_e32 v124, 0
	v_mov_b32_e32 v125, v137
	v_mov_b32_e32 v126, v137
	v_mov_b32_e32 v127, v137
	s_waitcnt vmcnt(0) lgkmcnt(0)
	s_barrier
	s_and_b32 s21, s13, 0x10000
	s_xor_b32 s24, s21, 0x10000
	s_add_i32 s24, s11, s24
	s_add_i32 s25, s24, 0x8000
	s_mov_b32 m0, s24
	v_lshl_add_u64 v[254:255], v[154:155], 0, s[6:7]
	global_load_lds_dwordx4 v[254:255], off
	s_add_i32 m0, s24, 0x2000
	v_lshl_add_u64 v[254:255], v[156:157], 0, s[6:7]
	global_load_lds_dwordx4 v[254:255], off
	s_add_i32 m0, s24, 0x4000
	v_lshl_add_u64 v[254:255], v[158:159], 0, s[6:7]
	global_load_lds_dwordx4 v[254:255], off
	s_add_i32 m0, s24, 0x6000
	v_lshl_add_u64 v[254:255], v[160:161], 0, s[6:7]
	global_load_lds_dwordx4 v[254:255], off
	s_mov_b32 m0, s25
	v_lshl_add_u64 v[254:255], v[162:163], 0, s[6:7]
	global_load_lds_dwordx4 v[254:255], off
	s_add_i32 m0, s24, 0xa000
	v_lshl_add_u64 v[254:255], v[164:165], 0, s[6:7]
	global_load_lds_dwordx4 v[254:255], off
	s_add_i32 m0, s24, 0xc000
	v_lshl_add_u64 v[254:255], v[166:167], 0, s[6:7]
	global_load_lds_dwordx4 v[254:255], off
	s_add_i32 m0, s24, 0xe000
	v_lshl_add_u64 v[254:255], v[168:169], 0, s[6:7]
	global_load_lds_dwordx4 v[254:255], off
	v_add3_u32 v253, s21, v141, v129
	ds_read_b128 v[206:209], v253 offset:0x1000
	ds_read_b128 v[210:213], v253 offset:0x1800
	ds_read_b128 v[198:201], v253 offset:0
	v_add3_u32 v253, s21, v143, v129
	ds_read_b128 v[170:173], v253 offset:0
	v_add3_u32 v253, s21, v141, v129
	ds_read_b128 v[202:205], v253 offset:0x800
	v_add3_u32 v253, s21, v143, v129
	ds_read_b128 v[174:177], v253 offset:0x800
	ds_read_b128 v[178:181], v253 offset:0x1000
	ds_read_b128 v[182:185], v253 offset:0x1800
	.p2align 6

.LBB0_1461:
	v_readfirstlane_b32 s11, v128
	s_lshr_b32 s12, s11, 1
	s_and_b32 s12, s12, 0x1ffff80
	s_lshl_b32 s0, s10, 19
	v_or_b32_e32 v5, s12, v189
	s_and_b32 s12, s11, 0xc0
	s_lshl_b32 s11, s11, 4
	v_add_u32_e32 v2, s0, v134
	v_lshlrev_b32_e32 v167, 7, v5
	v_or_b32_e32 v5, s12, v189
	s_and_b32 s11, s11, 0x7ffffc00
	v_add_u32_e32 v0, s0, v138
	v_lshl_or_b32 v203, v5, 7, v165
	v_and_b32_e32 v5, 0xfffff870, v2
	s_mov_b32 m0, s11
	v_add_u32_e32 v1, s0, v140
	global_load_lds_dwordx4 v5, s[86:87]
	v_and_b32_e32 v0, 0xfffff870, v0
	s_add_i32 m0, s11, 0x2000
	s_lshl_b32 s1, s30, 19
	v_add_u32_e32 v3, s0, v142
	global_load_lds_dwordx4 v0, s[86:87]
	v_and_b32_e32 v0, 0xfffff870, v1
	s_add_i32 m0, s11, 0x4000
	s_add_i32 s8, s1, 0x1080000
	global_load_lds_dwordx4 v0, s[86:87]
	v_and_b32_e32 v0, 0xfffff870, v3
	s_add_i32 m0, s11, 0x6000
	s_add_i32 s12, s11, 0x8000
	global_load_lds_dwordx4 v0, s[86:87]
	v_or_b32_e32 v0, s8, v144
	v_mov_b32_e32 v1, v145
	v_lshl_add_u64 v[0:1], s[86:87], 0, v[0:1]
	s_mov_b32 m0, s12
	v_add_u32_e32 v4, s1, v150
	global_load_lds_dwordx4 v[0:1], off
	v_or_b32_e32 v0, s8, v146
	v_mov_b32_e32 v1, v129
	v_lshl_add_u64 v[0:1], s[86:87], 0, v[0:1]
	s_add_i32 m0, s11, 0xa000
	v_and_b32_e32 v136, -16, v2
	global_load_lds_dwordx4 v[0:1], off
	v_or_b32_e32 v0, s8, v148
	v_mov_b32_e32 v1, v149
	v_lshl_add_u64 v[0:1], s[86:87], 0, v[0:1]
	s_add_i32 m0, s11, 0xc000
	v_lshl_add_u64 v[168:169], s[6:7], 0, v[136:137]
	global_load_lds_dwordx4 v[0:1], off
	v_and_b32_e32 v0, 0xfffff870, v4
	s_add_i32 m0, s11, 0xe000
	v_mov_b32_e32 v52, 0
	global_load_lds_dwordx4 v0, s[86:87]
	v_add_u32_e32 v0, s0, v152
	v_and_b32_e32 v136, -16, v0
	v_add_u32_e32 v0, s0, v154
	v_lshl_add_u64 v[170:171], s[6:7], 0, v[136:137]
	v_and_b32_e32 v136, -16, v0
	v_add_u32_e32 v0, s0, v156
	s_waitcnt vmcnt(8)
	v_lshl_add_u64 v[172:173], s[6:7], 0, v[136:137]
	v_and_b32_e32 v136, -16, v0
	v_add_u32_e32 v0, s1, v164
	v_lshl_add_u64 v[174:175], s[6:7], 0, v[136:137]
	v_and_b32_e32 v136, -16, v0
	v_lshl_add_u64 v[176:177], v[158:159], 0, s[8:9]
	v_lshl_add_u64 v[178:179], v[160:161], 0, s[8:9]
	v_lshl_add_u64 v[180:181], v[162:163], 0, s[8:9]
	v_lshl_add_u64 v[182:183], s[6:7], 0, v[136:137]
	s_mov_b32 s8, 0
	s_mov_b64 s[0:1], 0
	v_mov_b32_e32 v53, v52
	v_mov_b32_e32 v54, v52
	v_mov_b32_e32 v55, v52
	v_mov_b32_e32 v0, v52
	v_mov_b32_e32 v1, v52
	v_mov_b32_e32 v2, v52
	v_mov_b32_e32 v3, v52
	v_mov_b32_e32 v64, v52
	v_mov_b32_e32 v65, v52
	v_mov_b32_e32 v66, v52
	v_mov_b32_e32 v67, v52
	v_mov_b32_e32 v68, v52
	v_mov_b32_e32 v69, v52
	v_mov_b32_e32 v70, v52
	v_mov_b32_e32 v71, v52
	v_mov_b32_e32 v4, v52
	v_mov_b32_e32 v5, v52
	v_mov_b32_e32 v6, v52
	v_mov_b32_e32 v7, v52
	v_mov_b32_e32 v8, v52
	v_mov_b32_e32 v9, v52
	v_mov_b32_e32 v10, v52
	v_mov_b32_e32 v11, v52
	v_mov_b32_e32 v72, v52
	v_mov_b32_e32 v73, v52
	v_mov_b32_e32 v74, v52
	v_mov_b32_e32 v75, v52
	v_mov_b32_e32 v76, v52
	v_mov_b32_e32 v77, v52
	v_mov_b32_e32 v78, v52
	v_mov_b32_e32 v79, v52
	v_mov_b32_e32 v12, v52
	v_mov_b32_e32 v13, v52
	v_mov_b32_e32 v14, v52
	v_mov_b32_e32 v15, v52
	v_mov_b32_e32 v16, v52
	v_mov_b32_e32 v17, v52
	v_mov_b32_e32 v18, v52
	v_mov_b32_e32 v19, v52
	v_mov_b32_e32 v80, v52
	v_mov_b32_e32 v81, v52
	v_mov_b32_e32 v82, v52
	v_mov_b32_e32 v83, v52
	v_mov_b32_e32 v84, v52
	v_mov_b32_e32 v85, v52
	v_mov_b32_e32 v86, v52
	v_mov_b32_e32 v87, v52
	v_mov_b32_e32 v20, v52
	v_mov_b32_e32 v21, v52
	v_mov_b32_e32 v22, v52
	v_mov_b32_e32 v23, v52
	v_mov_b32_e32 v24, v52
	v_mov_b32_e32 v25, v52
	v_mov_b32_e32 v26, v52
	v_mov_b32_e32 v27, v52
	v_mov_b32_e32 v88, v52
	v_mov_b32_e32 v89, v52
	v_mov_b32_e32 v90, v52
	v_mov_b32_e32 v91, v52
	v_mov_b32_e32 v92, v52
	v_mov_b32_e32 v93, v52
	v_mov_b32_e32 v94, v52
	v_mov_b32_e32 v95, v52
	v_mov_b32_e32 v28, v52
	v_mov_b32_e32 v29, v52
	v_mov_b32_e32 v30, v52
	v_mov_b32_e32 v31, v52
	v_mov_b32_e32 v32, v52
	v_mov_b32_e32 v33, v52
	v_mov_b32_e32 v34, v52
	v_mov_b32_e32 v35, v52
	v_mov_b32_e32 v96, v52
	v_mov_b32_e32 v97, v52
	v_mov_b32_e32 v98, v52
	v_mov_b32_e32 v99, v52
	v_mov_b32_e32 v100, v52
	v_mov_b32_e32 v101, v52
	v_mov_b32_e32 v102, v52
	v_mov_b32_e32 v103, v52
	v_mov_b32_e32 v36, v52
	v_mov_b32_e32 v37, v52
	v_mov_b32_e32 v38, v52
	v_mov_b32_e32 v39, v52
	v_mov_b32_e32 v40, v52
	v_mov_b32_e32 v41, v52
	v_mov_b32_e32 v42, v52
	v_mov_b32_e32 v43, v52
	v_mov_b32_e32 v104, v52
	v_mov_b32_e32 v105, v52
	v_mov_b32_e32 v106, v52
	v_mov_b32_e32 v107, v52
	v_mov_b32_e32 v108, v52
	v_mov_b32_e32 v109, v52
	v_mov_b32_e32 v110, v52
	v_mov_b32_e32 v111, v52
	v_mov_b32_e32 v44, v52
	v_mov_b32_e32 v45, v52
	v_mov_b32_e32 v46, v52
	v_mov_b32_e32 v47, v52
	v_mov_b32_e32 v48, v52
	v_mov_b32_e32 v49, v52
	v_mov_b32_e32 v50, v52
	v_mov_b32_e32 v51, v52
	v_mov_b32_e32 v112, v52
	v_mov_b32_e32 v113, v52
	v_mov_b32_e32 v114, v52
	v_mov_b32_e32 v115, v52
	v_mov_b32_e32 v116, v52
	v_mov_b32_e32 v117, v52
	v_mov_b32_e32 v118, v52
	v_mov_b32_e32 v119, v52
	v_mov_b32_e32 v56, v52
	v_mov_b32_e32 v57, v52
	v_mov_b32_e32 v58, v52
	v_mov_b32_e32 v59, v52
	v_mov_b32_e32 v60, v52
	v_mov_b32_e32 v61, v52
	v_mov_b32_e32 v62, v52
	v_mov_b32_e32 v63, v52
	v_mov_b32_e32 v120, v52
	v_mov_b32_e32 v121, v52
	v_mov_b32_e32 v122, v52
	v_mov_b32_e32 v123, v52
	v_mov_b32_e32 v124, v52
	v_mov_b32_e32 v125, v52
	v_mov_b32_e32 v126, v52
	v_mov_b32_e32 v127, v52
	s_waitcnt vmcnt(0) lgkmcnt(0)
	s_barrier
	s_mov_b32 s12, 0x10000
	s_and_b32 s12, s8, 0x10000
	s_xor_b32 s13, s12, 0x10000
	s_add_i32 s13, s11, s13
	s_add_i32 s31, s13, 0x8000
	s_mov_b32 m0, s13
	v_lshl_add_u64 v[254:255], v[168:169], 0, s[0:1]
	global_load_lds_dwordx4 v[254:255], off
	s_add_i32 m0, s13, 0x2000
	v_lshl_add_u64 v[254:255], v[170:171], 0, s[0:1]
	global_load_lds_dwordx4 v[254:255], off
	s_add_i32 m0, s13, 0x4000
	v_lshl_add_u64 v[254:255], v[172:173], 0, s[0:1]
	global_load_lds_dwordx4 v[254:255], off
	s_add_i32 m0, s13, 0x6000
	v_lshl_add_u64 v[254:255], v[174:175], 0, s[0:1]
	global_load_lds_dwordx4 v[254:255], off
	s_mov_b32 m0, s31
	v_lshl_add_u64 v[254:255], v[176:177], 0, s[0:1]
	global_load_lds_dwordx4 v[254:255], off
	s_add_i32 m0, s13, 0xa000
	v_lshl_add_u64 v[254:255], v[178:179], 0, s[0:1]
	global_load_lds_dwordx4 v[254:255], off
	s_add_i32 m0, s13, 0xc000
	v_lshl_add_u64 v[254:255], v[180:181], 0, s[0:1]
	global_load_lds_dwordx4 v[254:255], off
	s_add_i32 m0, s13, 0xe000
	v_lshl_add_u64 v[254:255], v[182:183], 0, s[0:1]
	global_load_lds_dwordx4 v[254:255], off
	v_add3_u32 v253, s12, v167, v139
	ds_read_b128 v[228:231], v253 offset:0x1000
	ds_read_b128 v[232:235], v253 offset:0x1800
	ds_read_b128 v[220:223], v253 offset:0
	v_add3_u32 v253, s12, v203, v139
	ds_read_b128 v[204:207], v253 offset:0
	v_add3_u32 v253, s12, v167, v139
	ds_read_b128 v[224:227], v253 offset:0x800
	v_add3_u32 v253, s12, v203, v139
	ds_read_b128 v[208:211], v253 offset:0x800
	ds_read_b128 v[212:215], v253 offset:0x1000
	ds_read_b128 v[216:219], v253 offset:0x1800
	.p2align 6

.LBB0_1857:
	s_ashr_i32 s0, s24, 31
	s_lshr_b32 s0, s0, 26
	s_add_i32 s0, s24, s0
	v_readfirstlane_b32 s13, v128
	s_ashr_i32 s14, s0, 6
	s_andn2_b32 s0, s0, 63
	s_lshr_b32 s15, s13, 1
	s_sub_i32 s12, s24, s0
	s_and_b32 s15, s15, 0x1ffff80
	s_lshl_b32 s0, s12, 19
	v_or_b32_e32 v5, s15, v189
	s_and_b32 s15, s13, 0xc0
	s_lshl_b32 s13, s13, 4
	v_add_u32_e32 v2, s0, v136
	v_lshlrev_b32_e32 v149, 7, v5
	v_or_b32_e32 v5, s15, v189
	s_and_b32 s13, s13, 0x7ffffc00
	v_add_u32_e32 v0, s0, v140
	v_lshl_or_b32 v153, v5, 7, v133
	v_and_b32_e32 v5, 0xfffff870, v2
	s_mov_b32 m0, s13
	v_add_u32_e32 v1, s0, v142
	global_load_lds_dwordx4 v5, s[86:87]
	v_and_b32_e32 v0, 0xfffff870, v0
	s_add_i32 m0, s13, 0x2000
	s_lshl_b32 s1, s14, 19
	v_add_u32_e32 v3, s0, v144
	global_load_lds_dwordx4 v0, s[86:87]
	v_and_b32_e32 v0, 0xfffff870, v1
	s_add_i32 m0, s13, 0x4000
	s_add_i32 s10, s1, 0x1700000
	global_load_lds_dwordx4 v0, s[86:87]
	v_and_b32_e32 v0, 0xfffff870, v3
	s_add_i32 m0, s13, 0x6000
	s_add_i32 s15, s13, 0x8000
	global_load_lds_dwordx4 v0, s[86:87]
	v_or_b32_e32 v0, s10, v146
	v_mov_b32_e32 v1, v147
	v_lshl_add_u64 v[0:1], s[86:87], 0, v[0:1]
	s_mov_b32 m0, s15
	v_add_u32_e32 v4, s1, v152
	global_load_lds_dwordx4 v[0:1], off
	v_or_b32_e32 v0, s10, v148
	v_mov_b32_e32 v1, v129
	v_lshl_add_u64 v[0:1], s[86:87], 0, v[0:1]
	s_add_i32 m0, s13, 0xa000
	v_and_b32_e32 v138, -16, v2
	global_load_lds_dwordx4 v[0:1], off
	v_or_b32_e32 v0, s10, v150
	v_mov_b32_e32 v1, v131
	v_lshl_add_u64 v[0:1], s[86:87], 0, v[0:1]
	s_add_i32 m0, s13, 0xc000
	v_lshl_add_u64 v[170:171], s[8:9], 0, v[138:139]
	global_load_lds_dwordx4 v[0:1], off
	v_and_or_b32 v0, v4, s17, v134
	v_mov_b32_e32 v1, v135
	v_lshl_add_u64 v[0:1], s[86:87], 0, v[0:1]
	s_add_i32 m0, s13, 0xe000
	v_lshl_add_u64 v[178:179], v[160:161], 0, s[10:11]
	global_load_lds_dwordx4 v[0:1], off
	v_add_u32_e32 v0, s0, v154
	v_and_b32_e32 v138, -16, v0
	v_add_u32_e32 v0, s0, v156
	v_lshl_add_u64 v[172:173], s[8:9], 0, v[138:139]
	v_and_b32_e32 v138, -16, v0
	v_add_u32_e32 v0, s0, v158
	s_waitcnt vmcnt(8)
	v_lshl_add_u64 v[174:175], s[8:9], 0, v[138:139]
	v_and_b32_e32 v138, -16, v0
	v_add_u32_e32 v0, s1, v168
	v_lshl_add_u64 v[176:177], s[8:9], 0, v[138:139]
	v_and_b32_e32 v138, 0xfffff800, v0
	v_lshl_add_u64 v[180:181], v[162:163], 0, s[10:11]
	v_lshl_add_u64 v[182:183], v[164:165], 0, s[10:11]
	v_lshl_add_u64 v[184:185], v[166:167], 0, v[138:139]
	s_mov_b64 s[0:1], 0
	s_mov_b32 s10, 0
	s_mov_b32 s15, 0
	v_mov_b32_e32 v56, 0
	v_mov_b32_e32 v57, v139
	v_mov_b32_e32 v58, v139
	v_mov_b32_e32 v59, v139
	v_mov_b32_e32 v52, 0
	v_mov_b32_e32 v53, v139
	v_mov_b32_e32 v54, v139
	v_mov_b32_e32 v55, v139
	v_mov_b32_e32 v64, 0
	v_mov_b32_e32 v65, v139
	v_mov_b32_e32 v66, v139
	v_mov_b32_e32 v67, v139
	v_mov_b32_e32 v68, 0
	v_mov_b32_e32 v69, v139
	v_mov_b32_e32 v70, v139
	v_mov_b32_e32 v71, v139
	v_mov_b32_e32 v0, 0
	v_mov_b32_e32 v1, v139
	v_mov_b32_e32 v2, v139
	v_mov_b32_e32 v3, v139
	v_mov_b32_e32 v4, 0
	v_mov_b32_e32 v5, v139
	v_mov_b32_e32 v6, v139
	v_mov_b32_e32 v7, v139
	v_mov_b32_e32 v72, 0
	v_mov_b32_e32 v73, v139
	v_mov_b32_e32 v74, v139
	v_mov_b32_e32 v75, v139
	v_mov_b32_e32 v76, 0
	v_mov_b32_e32 v77, v139
	v_mov_b32_e32 v78, v139
	v_mov_b32_e32 v79, v139
	v_mov_b32_e32 v8, 0
	v_mov_b32_e32 v9, v139
	v_mov_b32_e32 v10, v139
	v_mov_b32_e32 v11, v139
	v_mov_b32_e32 v12, 0
	v_mov_b32_e32 v13, v139
	v_mov_b32_e32 v14, v139
	v_mov_b32_e32 v15, v139
	v_mov_b32_e32 v80, 0
	v_mov_b32_e32 v81, v139
	v_mov_b32_e32 v82, v139
	v_mov_b32_e32 v83, v139
	v_mov_b32_e32 v84, 0
	v_mov_b32_e32 v85, v139
	v_mov_b32_e32 v86, v139
	v_mov_b32_e32 v87, v139
	v_mov_b32_e32 v16, 0
	v_mov_b32_e32 v17, v139
	v_mov_b32_e32 v18, v139
	v_mov_b32_e32 v19, v139
	v_mov_b32_e32 v20, 0
	v_mov_b32_e32 v21, v139
	v_mov_b32_e32 v22, v139
	v_mov_b32_e32 v23, v139
	v_mov_b32_e32 v88, 0
	v_mov_b32_e32 v89, v139
	v_mov_b32_e32 v90, v139
	v_mov_b32_e32 v91, v139
	v_mov_b32_e32 v92, 0
	v_mov_b32_e32 v93, v139
	v_mov_b32_e32 v94, v139
	v_mov_b32_e32 v95, v139
	v_mov_b32_e32 v24, 0
	v_mov_b32_e32 v25, v139
	v_mov_b32_e32 v26, v139
	v_mov_b32_e32 v27, v139
	v_mov_b32_e32 v28, 0
	v_mov_b32_e32 v29, v139
	v_mov_b32_e32 v30, v139
	v_mov_b32_e32 v31, v139
	v_mov_b32_e32 v96, 0
	v_mov_b32_e32 v97, v139
	v_mov_b32_e32 v98, v139
	v_mov_b32_e32 v99, v139
	v_mov_b32_e32 v100, 0
	v_mov_b32_e32 v101, v139
	v_mov_b32_e32 v102, v139
	v_mov_b32_e32 v103, v139
	v_mov_b32_e32 v32, 0
	v_mov_b32_e32 v33, v139
	v_mov_b32_e32 v34, v139
	v_mov_b32_e32 v35, v139
	v_mov_b32_e32 v36, 0
	v_mov_b32_e32 v37, v139
	v_mov_b32_e32 v38, v139
	v_mov_b32_e32 v39, v139
	v_mov_b32_e32 v104, 0
	v_mov_b32_e32 v105, v139
	v_mov_b32_e32 v106, v139
	v_mov_b32_e32 v107, v139
	v_mov_b32_e32 v108, 0
	v_mov_b32_e32 v109, v139
	v_mov_b32_e32 v110, v139
	v_mov_b32_e32 v111, v139
	v_mov_b32_e32 v40, 0
	v_mov_b32_e32 v41, v139
	v_mov_b32_e32 v42, v139
	v_mov_b32_e32 v43, v139
	v_mov_b32_e32 v44, 0
	v_mov_b32_e32 v45, v139
	v_mov_b32_e32 v46, v139
	v_mov_b32_e32 v47, v139
	v_mov_b32_e32 v112, 0
	v_mov_b32_e32 v113, v139
	v_mov_b32_e32 v114, v139
	v_mov_b32_e32 v115, v139
	v_mov_b32_e32 v116, 0
	v_mov_b32_e32 v117, v139
	v_mov_b32_e32 v118, v139
	v_mov_b32_e32 v119, v139
	v_mov_b32_e32 v48, 0
	v_mov_b32_e32 v49, v139
	v_mov_b32_e32 v50, v139
	v_mov_b32_e32 v51, v139
	v_mov_b32_e32 v60, 0
	v_mov_b32_e32 v61, v139
	v_mov_b32_e32 v62, v139
	v_mov_b32_e32 v63, v139
	v_mov_b32_e32 v120, 0
	v_mov_b32_e32 v121, v139
	v_mov_b32_e32 v122, v139
	v_mov_b32_e32 v123, v139
	v_mov_b32_e32 v124, 0
	v_mov_b32_e32 v125, v139
	v_mov_b32_e32 v126, v139
	v_mov_b32_e32 v127, v139
	s_waitcnt vmcnt(0) lgkmcnt(0)
	s_barrier
	s_and_b32 s25, s10, 0x10000
	s_xor_b32 s26, s25, 0x10000
	s_add_i32 s26, s13, s26
	s_add_i32 s27, s26, 0x8000
	s_mov_b32 m0, s26
	v_lshl_add_u64 v[254:255], v[170:171], 0, s[0:1]
	global_load_lds_dwordx4 v[254:255], off
	s_add_i32 m0, s26, 0x2000
	v_lshl_add_u64 v[254:255], v[172:173], 0, s[0:1]
	global_load_lds_dwordx4 v[254:255], off
	s_add_i32 m0, s26, 0x4000
	v_lshl_add_u64 v[254:255], v[174:175], 0, s[0:1]
	global_load_lds_dwordx4 v[254:255], off
	s_add_i32 m0, s26, 0x6000
	v_lshl_add_u64 v[254:255], v[176:177], 0, s[0:1]
	global_load_lds_dwordx4 v[254:255], off
	s_mov_b32 m0, s27
	v_lshl_add_u64 v[254:255], v[178:179], 0, s[0:1]
	global_load_lds_dwordx4 v[254:255], off
	s_add_i32 m0, s26, 0xa000
	v_lshl_add_u64 v[254:255], v[180:181], 0, s[0:1]
	global_load_lds_dwordx4 v[254:255], off
	s_add_i32 m0, s26, 0xc000
	v_lshl_add_u64 v[254:255], v[182:183], 0, s[0:1]
	global_load_lds_dwordx4 v[254:255], off
	s_add_i32 m0, s26, 0xe000
	v_lshl_add_u64 v[254:255], v[184:185], 0, s[0:1]
	global_load_lds_dwordx4 v[254:255], off
	v_add3_u32 v253, s25, v149, v137
	ds_read_b128 v[224:227], v253 offset:0x1000
	ds_read_b128 v[228:231], v253 offset:0x1800
	ds_read_b128 v[216:219], v253 offset:0
	v_add3_u32 v253, s25, v153, v137
	ds_read_b128 v[200:203], v253 offset:0
	v_add3_u32 v253, s25, v149, v137
	ds_read_b128 v[220:223], v253 offset:0x800
	v_add3_u32 v253, s25, v153, v137
	ds_read_b128 v[204:207], v253 offset:0x800
	ds_read_b128 v[208:211], v253 offset:0x1000
	ds_read_b128 v[212:215], v253 offset:0x1800
	.p2align 6

.LBB0_1988:
	s_mul_hi_i32 s0, s31, 0x78787879
	s_lshr_b32 s1, s0, 31
	s_ashr_i32 s20, s0, 5
	s_add_i32 s20, s20, s1
	s_mul_i32 s0, s20, 0x44
	s_sub_i32 s0, s31, s0
	s_lshl_b32 s21, s0, 1
	v_or_b32_e32 v0, s21, v135
	v_cmp_lt_i32_e32 vcc, s17, v0
	s_and_saveexec_b64 s[0:1], vcc
	s_xor_b64 s[0:1], exec, s[0:1]
	v_add_u32_e32 v0, 0xffffff78, v0
	v_mul_hi_u32 v1, v0, s24
	v_lshrrev_b32_e32 v2, 1, v1
	v_lshl_add_u32 v1, v2, 8, v159
	v_lshl_add_u32 v2, v2, 1, v2
	v_sub_u32_e32 v3, v0, v2
	s_or_saveexec_b64 s[0:1], s[0:1]
	v_mov_b32_e32 v2, 0x100
	s_xor_b64 exec, exec, s[0:1]
	v_mul_hi_i32 v1, v0, s16
	v_lshrrev_b32_e32 v2, 31, v1
	v_ashrrev_i32_e32 v1, 3, v1
	v_add_u32_e32 v2, v1, v2
	v_lshlrev_b32_e32 v1, 11, v2
	v_lshl_add_u32 v2, v2, 4, v2
	v_sub_u32_e32 v3, v0, v2
	v_mov_b32_e32 v2, 0x800
	s_or_b64 exec, exec, s[0:1]
	s_or_b32 s6, s21, 1
	s_cmpk_gt_i32 s6, 0x87
	s_mov_b64 s[0:1], -1
	s_cbranch_scc0 .LBB0_1994
	s_add_i32 s7, s21, 0xffffff79
	s_mov_b64 s[0:1], 0

.LBB0_1997:
	v_add_u32_e32 v7, s21, v137
	v_cmp_gt_i32_e32 vcc, s25, v7
	v_mov_b32_e32 v0, 0
	v_mov_b32_e32 v4, 0x100
	v_mov_b32_e32 v5, 0x4000
	v_mov_b32_e32 v6, 0
	s_and_saveexec_b64 s[0:1], vcc
	v_mul_hi_i32 v4, v7, s16
	v_lshrrev_b32_e32 v5, 31, v4
	v_ashrrev_i32_e32 v4, 3, v4
	v_add_u32_e32 v4, v4, v5
	v_lshlrev_b32_e32 v5, 11, v4
	v_lshl_add_u32 v4, v4, 4, v4
	v_sub_u32_e32 v4, v7, v4
	v_mul_lo_u32 v6, v4, s26
	v_mov_b32_e32 v4, 0x800
	s_or_b64 exec, exec, s[0:1]
	s_mul_i32 s0, s7, 0x7e
	v_add_u32_e32 v7, s0, v129
	v_add_u32_e32 v8, s33, v7
	v_lshl_add_u32 v10, v8, 11, v134
	v_mad_u64_u32 v[8:9], s[0:1], v3, s26, v[136:137]
	s_mul_i32 s1, s21, 0x7879
	s_lshr_b32 s7, s1, 31
	s_ashr_i32 s1, s1, 19
	s_add_i32 s1, s1, s7
	s_mul_i32 s7, s1, 17
	s_sub_i32 s7, s21, s7
	s_mulk_i32 s7, 0x7e
	s_sext_i32_i16 s7, s7
	v_add_u32_e32 v3, s7, v129
	v_lshl_add_u32 v9, s1, 11, v3
	v_add_u32_e32 v1, v8, v1
	v_lshl_add_u32 v9, v9, 11, v134
	v_cmp_gt_u32_e32 vcc, s27, v3
	v_lshl_add_u32 v1, v1, 11, v138
	v_readfirstlane_b32 s1, v128
	v_cndmask_b32_e32 v3, v147, v9, vcc
	v_cmp_lt_u32_e32 vcc, v8, v2
	v_subrev_u32_e32 v132, s86, v3
	v_add_u32_e32 v11, v139, v6
	v_cndmask_b32_e32 v1, v147, v1, vcc
	v_cmp_gt_u32_e32 vcc, s6, v7
	s_lshr_b32 s6, s1, 1
	s_and_b32 s6, s6, 0x1ffff80
	v_or_b32_e32 v3, s6, v189
	s_and_b32 s6, s1, 0xc0
	s_lshl_b32 s1, s1, 4
	s_and_b32 s33, s1, 0x7ffffc00
	v_add_u32_e32 v5, v11, v5
	s_mov_b32 m0, s33
	v_lshl_add_u32 v5, v5, 11, v142
	v_subrev_u32_e32 v2, s86, v1
	v_cndmask_b32_e32 v1, v147, v10, vcc
	v_cmp_lt_u32_e32 vcc, v11, v4
	global_load_lds_dwordx4 v132, s[86:87]
	s_add_i32 m0, s33, 0x2000
	s_lshl_b32 s0, s20, 19
	v_subrev_u32_e32 v6, s86, v1
	v_cndmask_b32_e32 v1, v147, v5, vcc
	global_load_lds_dwordx4 v2, s[86:87]
	s_add_i32 m0, s33, 0x4000
	v_subrev_u32_e32 v4, s86, v1
	v_lshlrev_b32_e32 v178, 7, v3
	v_or_b32_e32 v3, s6, v189
	s_add_i32 s6, s33, 0x8000
	global_load_lds_dwordx4 v6, s[86:87]
	s_add_i32 m0, s33, 0x6000
	v_or_b32_e32 v8, s0, v146
	v_mov_b32_e32 v9, v133
	global_load_lds_dwordx4 v4, s[86:87]
	v_lshl_add_u64 v[8:9], s[86:87], 0, v[8:9]
	s_mov_b32 m0, s6
	v_add_u32_e32 v1, s0, v150
	global_load_lds_dwordx4 v[8:9], off
	v_or_b32_e32 v8, s0, v148
	v_mov_b32_e32 v9, v133
	v_add_u32_e32 v10, s0, v144
	v_lshl_add_u64 v[8:9], s[86:87], 0, v[8:9]
	s_add_i32 m0, s33, 0xa000
	v_and_b32_e32 v1, 0xfffff870, v1
	global_load_lds_dwordx4 v[8:9], off
	s_add_i32 m0, s33, 0xc000
	v_and_or_b32 v8, v10, s28, v140
	v_mov_b32_e32 v9, v141
	global_load_lds_dwordx4 v1, s[86:87]
	v_lshl_add_u64 v[8:9], s[86:87], 0, v[8:9]
	s_add_i32 m0, s33, 0xe000
	v_add_u32_e32 v1, s0, v154
	global_load_lds_dwordx4 v[8:9], off
	v_lshl_add_u64 v[160:161], s[18:19], 0, v[132:133]
	v_and_b32_e32 v132, -16, v1
	v_add_u32_e32 v1, s0, v158
	v_lshl_or_b32 v179, v3, 7, v149
	v_mov_b32_e32 v3, v133
	v_mov_b32_e32 v7, v133
	v_mov_b32_e32 v5, v133
	s_mov_b32 s1, 0
	v_lshl_add_u64 v[172:173], s[18:19], 0, v[132:133]
	v_and_b32_e32 v132, 0xfffff800, v1
	v_lshl_add_u64 v[162:163], s[18:19], 0, v[2:3]
	v_lshl_add_u64 v[164:165], s[18:19], 0, v[6:7]
	v_lshl_add_u64 v[166:167], s[18:19], 0, v[4:5]
	v_lshl_add_u64 v[168:169], v[152:153], 0, s[0:1]
	v_lshl_add_u64 v[170:171], v[130:131], 0, s[0:1]
	v_lshl_add_u64 v[174:175], v[156:157], 0, v[132:133]
	s_mov_b64 s[6:7], 0
	v_mov_b32_e32 v1, v0
	v_mov_b32_e32 v2, v0
	v_mov_b32_e32 v3, v0
	v_mov_b32_e32 v4, v0
	v_mov_b32_e32 v5, v0
	v_mov_b32_e32 v6, v0
	v_mov_b32_e32 v7, v0
	v_mov_b32_e32 v64, v0
	v_mov_b32_e32 v65, v0
	v_mov_b32_e32 v66, v0
	v_mov_b32_e32 v67, v0
	v_mov_b32_e32 v68, v0
	v_mov_b32_e32 v69, v0
	v_mov_b32_e32 v70, v0
	v_mov_b32_e32 v71, v0
	v_mov_b32_e32 v8, v0
	v_mov_b32_e32 v9, v0
	v_mov_b32_e32 v10, v0
	v_mov_b32_e32 v11, v0
	v_mov_b32_e32 v12, v0
	v_mov_b32_e32 v13, v0
	v_mov_b32_e32 v14, v0
	v_mov_b32_e32 v15, v0
	v_mov_b32_e32 v72, v0
	v_mov_b32_e32 v73, v0
	v_mov_b32_e32 v74, v0
	v_mov_b32_e32 v75, v0
	v_mov_b32_e32 v76, v0
	v_mov_b32_e32 v77, v0
	v_mov_b32_e32 v78, v0
	v_mov_b32_e32 v79, v0
	v_mov_b32_e32 v16, v0
	v_mov_b32_e32 v17, v0
	v_mov_b32_e32 v18, v0
	v_mov_b32_e32 v19, v0
	v_mov_b32_e32 v20, v0
	v_mov_b32_e32 v21, v0
	v_mov_b32_e32 v22, v0
	v_mov_b32_e32 v23, v0
	v_mov_b32_e32 v80, v0
	v_mov_b32_e32 v81, v0
	v_mov_b32_e32 v82, v0
	v_mov_b32_e32 v83, v0
	v_mov_b32_e32 v84, v0
	v_mov_b32_e32 v85, v0
	v_mov_b32_e32 v86, v0
	v_mov_b32_e32 v87, v0
	v_mov_b32_e32 v24, v0
	v_mov_b32_e32 v25, v0
	v_mov_b32_e32 v26, v0
	v_mov_b32_e32 v27, v0
	v_mov_b32_e32 v28, v0
	v_mov_b32_e32 v29, v0
	v_mov_b32_e32 v30, v0
	v_mov_b32_e32 v31, v0
	v_mov_b32_e32 v88, v0
	v_mov_b32_e32 v89, v0
	v_mov_b32_e32 v90, v0
	v_mov_b32_e32 v91, v0
	v_mov_b32_e32 v92, v0
	v_mov_b32_e32 v93, v0
	v_mov_b32_e32 v94, v0
	v_mov_b32_e32 v95, v0
	v_mov_b32_e32 v32, v0
	v_mov_b32_e32 v33, v0
	v_mov_b32_e32 v34, v0
	v_mov_b32_e32 v35, v0
	v_mov_b32_e32 v36, v0
	v_mov_b32_e32 v37, v0
	v_mov_b32_e32 v38, v0
	v_mov_b32_e32 v39, v0
	v_mov_b32_e32 v96, v0
	v_mov_b32_e32 v97, v0
	v_mov_b32_e32 v98, v0
	v_mov_b32_e32 v99, v0
	v_mov_b32_e32 v100, v0
	v_mov_b32_e32 v101, v0
	v_mov_b32_e32 v102, v0
	v_mov_b32_e32 v103, v0
	v_mov_b32_e32 v40, v0
	v_mov_b32_e32 v41, v0
	v_mov_b32_e32 v42, v0
	v_mov_b32_e32 v43, v0
	v_mov_b32_e32 v44, v0
	v_mov_b32_e32 v45, v0
	v_mov_b32_e32 v46, v0
	v_mov_b32_e32 v47, v0
	v_mov_b32_e32 v104, v0
	v_mov_b32_e32 v105, v0
	v_mov_b32_e32 v106, v0
	v_mov_b32_e32 v107, v0
	v_mov_b32_e32 v108, v0
	v_mov_b32_e32 v109, v0
	v_mov_b32_e32 v110, v0
	v_mov_b32_e32 v111, v0
	v_mov_b32_e32 v48, v0
	v_mov_b32_e32 v49, v0
	v_mov_b32_e32 v50, v0
	v_mov_b32_e32 v51, v0
	v_mov_b32_e32 v52, v0
	v_mov_b32_e32 v53, v0
	v_mov_b32_e32 v54, v0
	v_mov_b32_e32 v55, v0
	v_mov_b32_e32 v112, v0
	v_mov_b32_e32 v113, v0
	v_mov_b32_e32 v114, v0
	v_mov_b32_e32 v115, v0
	v_mov_b32_e32 v116, v0
	v_mov_b32_e32 v117, v0
	v_mov_b32_e32 v118, v0
	v_mov_b32_e32 v119, v0
	v_mov_b32_e32 v56, v0
	v_mov_b32_e32 v57, v0
	v_mov_b32_e32 v58, v0
	v_mov_b32_e32 v59, v0
	v_mov_b32_e32 v60, v0
	v_mov_b32_e32 v61, v0
	v_mov_b32_e32 v62, v0
	v_mov_b32_e32 v63, v0
	v_mov_b32_e32 v120, v0
	v_mov_b32_e32 v121, v0
	v_mov_b32_e32 v122, v0
	v_mov_b32_e32 v123, v0
	v_mov_b32_e32 v124, v0
	v_mov_b32_e32 v125, v0
	v_mov_b32_e32 v126, v0
	v_mov_b32_e32 v127, v0
	s_waitcnt vmcnt(0) lgkmcnt(0)
	s_barrier
	s_mov_b32 s0, 0x10000
	s_and_b32 s0, s1, 0x10000
	s_xor_b32 s34, s0, 0x10000
	s_add_i32 s34, s33, s34
	s_add_i32 s35, s34, 0x8000
	s_mov_b32 m0, s34
	v_lshl_add_u64 v[254:255], v[160:161], 0, s[6:7]
	global_load_lds_dwordx4 v[254:255], off
	s_add_i32 m0, s34, 0x2000
	v_lshl_add_u64 v[254:255], v[162:163], 0, s[6:7]
	global_load_lds_dwordx4 v[254:255], off
	s_add_i32 m0, s34, 0x4000
	v_lshl_add_u64 v[254:255], v[164:165], 0, s[6:7]
	global_load_lds_dwordx4 v[254:255], off
	s_add_i32 m0, s34, 0x6000
	v_lshl_add_u64 v[254:255], v[166:167], 0, s[6:7]
	global_load_lds_dwordx4 v[254:255], off
	s_mov_b32 m0, s35
	v_lshl_add_u64 v[254:255], v[168:169], 0, s[6:7]
	global_load_lds_dwordx4 v[254:255], off
	s_add_i32 m0, s34, 0xa000
	v_lshl_add_u64 v[254:255], v[170:171], 0, s[6:7]
	global_load_lds_dwordx4 v[254:255], off
	s_add_i32 m0, s34, 0xc000
	v_lshl_add_u64 v[254:255], v[172:173], 0, s[6:7]
	global_load_lds_dwordx4 v[254:255], off
	s_add_i32 m0, s34, 0xe000
	v_lshl_add_u64 v[254:255], v[174:175], 0, s[6:7]
	global_load_lds_dwordx4 v[254:255], off
	v_add3_u32 v253, s0, v178, v143
	ds_read_b128 v[220:223], v253 offset:0x1000
	ds_read_b128 v[224:227], v253 offset:0x1800
	ds_read_b128 v[212:215], v253 offset:0
	v_add3_u32 v253, s0, v179, v143
	ds_read_b128 v[180:183], v253 offset:0
	v_add3_u32 v253, s0, v178, v143
	ds_read_b128 v[216:219], v253 offset:0x800
	v_add3_u32 v253, s0, v179, v143
	ds_read_b128 v[200:203], v253 offset:0x800
	ds_read_b128 v[204:207], v253 offset:0x1000
	ds_read_b128 v[208:211], v253 offset:0x1800
	.p2align 6

.LBB0_2081:
	s_ashr_i32 s0, s2, 31
	s_lshr_b32 s0, s0, 26
	s_add_i32 s0, s2, s0
	s_ashr_i32 s10, s0, 6
	s_andn2_b32 s0, s0, 63
	s_sub_i32 s8, s2, s0
	s_mul_i32 s0, s8, 0xb0000
	v_readfirstlane_b32 s9, v128
	s_lshl_b32 s11, s0, 1
	v_or_b32_e32 v3, s0, v130
	s_lshr_b32 s0, s9, 1
	s_and_b32 s0, s0, 0x1ffff80
	v_lshl_add_u32 v4, v3, 1, v140
	v_or_b32_e32 v3, s0, v189
	s_and_b32 s0, s9, 0xc0
	v_lshlrev_b32_e32 v137, 7, v3
	v_or_b32_e32 v3, s0, v189
	s_lshl_b32 s0, s9, 4
	v_add_u32_e32 v0, s11, v134
	s_and_b32 s9, s0, 0x7ffffc00
	v_add_u32_e32 v1, s11, v136
	v_and_b32_e32 v132, 0xfffffe70, v0
	s_mov_b32 m0, s9
	v_add_u32_e32 v2, s11, v138
	global_load_lds_dwordx4 v132, s[86:87]
	v_and_b32_e32 v0, 0xfffffe70, v1
	s_add_i32 m0, s9, 0x2000
	s_mul_i32 s1, s10, 0x160000
	global_load_lds_dwordx4 v0, s[86:87]
	v_and_b32_e32 v2, 0xfffffe70, v2
	s_add_i32 m0, s9, 0x4000
	v_add_u32_e32 v6, s1, v142
	s_add_i32 s0, s9, 0x8000
	global_load_lds_dwordx4 v2, s[86:87]
	v_and_b32_e32 v4, 0xfffffe70, v4
	s_add_i32 m0, s9, 0x6000
	v_add_u32_e32 v8, s1, v144
	v_add_u32_e32 v12, s1, v148
	global_load_lds_dwordx4 v4, s[86:87]
	v_and_b32_e32 v6, 0xfffffe70, v6
	s_mov_b32 m0, s0
	v_add_u32_e32 v10, s1, v146
	global_load_lds_dwordx4 v6, s[86:87]
	v_and_b32_e32 v8, 0xfffffe70, v8
	s_add_i32 m0, s9, 0xa000
	v_and_b32_e32 v12, 0xfffffe00, v12
	global_load_lds_dwordx4 v8, s[86:87]
	v_and_b32_e32 v10, 0xfffffe70, v10
	s_add_i32 m0, s9, 0xc000
	v_or_b32_e32 v14, v150, v12
	v_mov_b32_e32 v15, v151
	global_load_lds_dwordx4 v10, s[86:87]
	v_lshl_add_u64 v[14:15], s[86:87], 0, v[14:15]
	s_add_i32 m0, s9, 0xe000
	v_lshl_or_b32 v139, v3, 7, v135
	global_load_lds_dwordx4 v[14:15], off
	s_waitcnt vmcnt(8)
	v_mov_b32_e32 v1, v133
	v_mov_b32_e32 v3, v133
	v_mov_b32_e32 v5, v133
	v_mov_b32_e32 v7, v133
	v_mov_b32_e32 v9, v133
	v_mov_b32_e32 v11, v133
	v_mov_b32_e32 v13, v133
	v_lshl_add_u64 v[154:155], s[6:7], 0, v[132:133]
	v_lshl_add_u64 v[156:157], s[6:7], 0, v[0:1]
	v_lshl_add_u64 v[158:159], s[6:7], 0, v[2:3]
	v_lshl_add_u64 v[160:161], s[6:7], 0, v[4:5]
	v_lshl_add_u64 v[162:163], s[6:7], 0, v[6:7]
	v_lshl_add_u64 v[164:165], s[6:7], 0, v[8:9]
	v_lshl_add_u64 v[166:167], s[6:7], 0, v[10:11]
	v_lshl_add_u64 v[168:169], v[152:153], 0, v[12:13]
	s_mov_b64 s[0:1], 0
	s_mov_b32 s11, 0
	s_mov_b32 s16, 0
	v_mov_b32_e32 v56, 0
	v_mov_b32_e32 v57, v133
	v_mov_b32_e32 v58, v133
	v_mov_b32_e32 v59, v133
	v_mov_b32_e32 v52, 0
	v_mov_b32_e32 v53, v133
	v_mov_b32_e32 v54, v133
	v_mov_b32_e32 v55, v133
	v_mov_b32_e32 v64, 0
	v_mov_b32_e32 v65, v133
	v_mov_b32_e32 v66, v133
	v_mov_b32_e32 v67, v133
	v_mov_b32_e32 v68, 0
	v_mov_b32_e32 v69, v133
	v_mov_b32_e32 v70, v133
	v_mov_b32_e32 v71, v133
	v_mov_b32_e32 v0, 0
	v_mov_b32_e32 v2, v133
	v_mov_b32_e32 v4, 0
	v_mov_b32_e32 v6, v133
	v_mov_b32_e32 v72, 0
	v_mov_b32_e32 v73, v133
	v_mov_b32_e32 v74, v133
	v_mov_b32_e32 v75, v133
	v_mov_b32_e32 v76, 0
	v_mov_b32_e32 v77, v133
	v_mov_b32_e32 v78, v133
	v_mov_b32_e32 v79, v133
	v_mov_b32_e32 v8, 0
	v_mov_b32_e32 v10, v133
	v_mov_b32_e32 v12, 0
	v_mov_b32_e32 v14, v133
	v_mov_b32_e32 v15, v133
	v_mov_b32_e32 v80, 0
	v_mov_b32_e32 v81, v133
	v_mov_b32_e32 v82, v133
	v_mov_b32_e32 v83, v133
	v_mov_b32_e32 v84, 0
	v_mov_b32_e32 v85, v133
	v_mov_b32_e32 v86, v133
	v_mov_b32_e32 v87, v133
	v_mov_b32_e32 v16, 0
	v_mov_b32_e32 v17, v133
	v_mov_b32_e32 v18, v133
	v_mov_b32_e32 v19, v133
	v_mov_b32_e32 v20, 0
	v_mov_b32_e32 v21, v133
	v_mov_b32_e32 v22, v133
	v_mov_b32_e32 v23, v133
	v_mov_b32_e32 v88, 0
	v_mov_b32_e32 v89, v133
	v_mov_b32_e32 v90, v133
	v_mov_b32_e32 v91, v133
	v_mov_b32_e32 v92, 0
	v_mov_b32_e32 v93, v133
	v_mov_b32_e32 v94, v133
	v_mov_b32_e32 v95, v133
	v_mov_b32_e32 v24, 0
	v_mov_b32_e32 v25, v133
	v_mov_b32_e32 v26, v133
	v_mov_b32_e32 v27, v133
	v_mov_b32_e32 v28, 0
	v_mov_b32_e32 v29, v133
	v_mov_b32_e32 v30, v133
	v_mov_b32_e32 v31, v133
	v_mov_b32_e32 v96, 0
	v_mov_b32_e32 v97, v133
	v_mov_b32_e32 v98, v133
	v_mov_b32_e32 v99, v133
	v_mov_b32_e32 v100, 0
	v_mov_b32_e32 v101, v133
	v_mov_b32_e32 v102, v133
	v_mov_b32_e32 v103, v133
	v_mov_b32_e32 v32, 0
	v_mov_b32_e32 v33, v133
	v_mov_b32_e32 v34, v133
	v_mov_b32_e32 v35, v133
	v_mov_b32_e32 v36, 0
	v_mov_b32_e32 v37, v133
	v_mov_b32_e32 v38, v133
	v_mov_b32_e32 v39, v133
	v_mov_b32_e32 v104, 0
	v_mov_b32_e32 v105, v133
	v_mov_b32_e32 v106, v133
	v_mov_b32_e32 v107, v133
	v_mov_b32_e32 v108, 0
	v_mov_b32_e32 v109, v133
	v_mov_b32_e32 v110, v133
	v_mov_b32_e32 v111, v133
	v_mov_b32_e32 v40, 0
	v_mov_b32_e32 v41, v133
	v_mov_b32_e32 v42, v133
	v_mov_b32_e32 v43, v133
	v_mov_b32_e32 v44, 0
	v_mov_b32_e32 v45, v133
	v_mov_b32_e32 v46, v133
	v_mov_b32_e32 v47, v133
	v_mov_b32_e32 v112, 0
	v_mov_b32_e32 v113, v133
	v_mov_b32_e32 v114, v133
	v_mov_b32_e32 v115, v133
	v_mov_b32_e32 v116, 0
	v_mov_b32_e32 v117, v133
	v_mov_b32_e32 v118, v133
	v_mov_b32_e32 v119, v133
	v_mov_b32_e32 v48, 0
	v_mov_b32_e32 v49, v133
	v_mov_b32_e32 v50, v133
	v_mov_b32_e32 v51, v133
	v_mov_b32_e32 v60, 0
	v_mov_b32_e32 v61, v133
	v_mov_b32_e32 v62, v133
	v_mov_b32_e32 v63, v133
	v_mov_b32_e32 v120, 0
	v_mov_b32_e32 v121, v133
	v_mov_b32_e32 v122, v133
	v_mov_b32_e32 v123, v133
	v_mov_b32_e32 v124, 0
	v_mov_b32_e32 v125, v133
	v_mov_b32_e32 v126, v133
	v_mov_b32_e32 v127, v133
	s_waitcnt vmcnt(0) lgkmcnt(0)
	s_barrier
	s_and_b32 s17, s11, 0x10000
	s_xor_b32 s18, s17, 0x10000
	s_add_i32 s18, s9, s18
	s_add_i32 s19, s18, 0x8000
	s_mov_b32 m0, s18
	v_lshl_add_u64 v[254:255], v[154:155], 0, s[0:1]
	global_load_lds_dwordx4 v[254:255], off
	s_add_i32 m0, s18, 0x2000
	v_lshl_add_u64 v[254:255], v[156:157], 0, s[0:1]
	global_load_lds_dwordx4 v[254:255], off
	s_add_i32 m0, s18, 0x4000
	v_lshl_add_u64 v[254:255], v[158:159], 0, s[0:1]
	global_load_lds_dwordx4 v[254:255], off
	s_add_i32 m0, s18, 0x6000
	v_lshl_add_u64 v[254:255], v[160:161], 0, s[0:1]
	global_load_lds_dwordx4 v[254:255], off
	s_mov_b32 m0, s19
	v_lshl_add_u64 v[254:255], v[162:163], 0, s[0:1]
	global_load_lds_dwordx4 v[254:255], off
	s_add_i32 m0, s18, 0xa000
	v_lshl_add_u64 v[254:255], v[164:165], 0, s[0:1]
	global_load_lds_dwordx4 v[254:255], off
	s_add_i32 m0, s18, 0xc000
	v_lshl_add_u64 v[254:255], v[166:167], 0, s[0:1]
	global_load_lds_dwordx4 v[254:255], off
	s_add_i32 m0, s18, 0xe000
	v_lshl_add_u64 v[254:255], v[168:169], 0, s[0:1]
	global_load_lds_dwordx4 v[254:255], off
	v_add3_u32 v253, s17, v137, v129
	ds_read_b128 v[198:201], v253 offset:0x1000
	ds_read_b128 v[202:205], v253 offset:0x1800
	ds_read_b128 v[190:193], v253 offset:0
	v_add3_u32 v253, s17, v139, v129
	ds_read_b128 v[170:173], v253 offset:0
	v_add3_u32 v253, s17, v137, v129
	ds_read_b128 v[194:197], v253 offset:0x800
	v_add3_u32 v253, s17, v139, v129
	ds_read_b128 v[174:177], v253 offset:0x800
	ds_read_b128 v[178:181], v253 offset:0x1000
	ds_read_b128 v[182:185], v253 offset:0x1800
	.p2align 6
